# LRU items: second direction's gate biases / lambda loaded together with the first direction's (early) instead of right before use
# baseline (speedup 1.0000x reference)
; DEVI u16 f2bf(float x) { return (u16)(pk_bf16(x, 0.f) & 0xffffu); }
; DEVI void lru_item(const Params& p, int l, int item, int pass) {
;     ...
;   float uo[16];
;   { const float* cw = p.in[11] + (size_t)l * 4 * 256 + c;
;     const float w0 = cw[0], w1 = cw[256], w2 = cw[512], w3 = cw[768], cb = p.in[12][l * 256 + c];
;     const float* xr = xs + e * 145 + 8 + 16 * tg;
; #pragma unroll
;     for (int tt = 0; tt < 16; ++tt) { const float u = cb + w0 * xr[tt - 2] + w1 * xr[tt - 1] + w2 * xr[tt] + w3 * xr[tt + 1]; uo[tt] = u; ub[(16 * tg + tt) * 72 + e] = f2bf(u); } }
.LBB0_1294:
	s_or_b64 exec, exec, s[4:5]
	v_and_b32_e32 v55, 63, v53
	v_readlane_b32 s44, v252, 30
	s_waitcnt vmcnt(0)
	v_or_b32_e32 v11, s13, v55
	v_readlane_b32 s52, v252, 38
	v_readlane_b32 s53, v252, 39
	v_or_b32_e32 v212, s36, v11
	s_mov_b64 s[16:17], s[52:53]
	v_lshlrev_b32_e32 v1, 2, v11
	v_lshl_add_u64 v[4:5], v[212:213], 2, s[16:17]
	s_waitcnt lgkmcnt(0)
	s_barrier
	global_load_dword v2, v1, s[22:23]
	global_load_dword v3, v1, s[22:23] offset:1024
	global_load_dword v0, v1, s[22:23] offset:2048
	s_nop 0
	global_load_dword v1, v1, s[22:23] offset:3072
	s_movk_i32 s1, 0x244
	global_load_dword v69, v[4:5], off
	v_mad_u32_u24 v6, v55, s1, 0
	v_and_b32_e32 v4, 0xffffffc0, v54
	v_add_u32_e32 v7, v6, v4
	ds_read2_b32 v[4:5], v7 offset0:6 offset1:7
	v_ashrrev_i32_e32 v52, 6, v54
	s_movk_i32 s1, 0x900
	v_mul_i32_i24_e32 v8, 0xfffffdbe, v55
	v_and_b32_e32 v10, 15, v53
	v_readlane_b32 s4, v252, 63
	v_and_b32_e32 v212, 48, v53
	v_readlane_b32 s5, v253, 0
	s_lshl_b32 s0, s0, 13
	s_or_b32 s90, s0, s41
	v_lshlrev_b32_e32 v73, 6, v10
	v_or_b32_e32 v34, s37, v11
	v_or_b32_e32 v13, 0x800, v73
	v_lshlrev_b32_e32 v30, 1, v13
	v_mov_b32_e32 v31, v213
	v_or_b32_e32 v13, 0xc00, v73
	v_lshlrev_b32_e32 v32, 1, v13
	v_mov_b32_e32 v33, v213
	v_bfe_u32 v82, v53, 4, 2
	s_movk_i32 s0, 0x410
	v_or_b32_e32 v35, 0x400, v73
	v_readlane_b32 s45, v252, 31
	v_readlane_b32 s46, v252, 32
	v_readlane_b32 s47, v252, 33
	v_readlane_b32 s48, v252, 34
	v_readlane_b32 s49, v252, 35
	v_readlane_b32 s50, v252, 36
	v_readlane_b32 s51, v252, 37
	v_readlane_b32 s54, v252, 40
	v_readlane_b32 s55, v252, 41
	v_readlane_b32 s56, v252, 42
	v_readlane_b32 s57, v252, 43
	v_readlane_b32 s58, v252, 44
	v_readlane_b32 s59, v252, 45
	s_mov_b64 s[20:21], s[56:57]
	v_readlane_b32 s44, v252, 46
	v_readlane_b32 s45, v252, 47
	v_readlane_b32 s46, v252, 48
	v_readlane_b32 s47, v252, 49
	v_readlane_b32 s48, v252, 50
	v_readlane_b32 s49, v252, 51
	v_readlane_b32 s50, v252, 52
	v_readlane_b32 s51, v252, 53
	v_readlane_b32 s52, v252, 54
	v_readlane_b32 s53, v252, 55
	v_readlane_b32 s54, v252, 56
	v_readlane_b32 s55, v252, 57
	v_readlane_b32 s56, v252, 58
	v_readlane_b32 s57, v252, 59
	v_readlane_b32 s58, v252, 60
	v_readlane_b32 s59, v252, 61
	s_waitcnt vmcnt(0) lgkmcnt(0)
	v_fma_f32 v56, v2, v4, v69
	v_fmac_f32_e32 v56, v3, v5
	ds_read2_b32 v[4:5], v7 offset0:8 offset1:9
	s_waitcnt lgkmcnt(0)
	v_fmac_f32_e32 v56, v0, v4
	v_fmac_f32_e32 v56, v1, v5
	v_mul_lo_u32 v5, v52, s1
	v_cvt_pk_bf16_f32 v4, v56, v213
	v_add3_u32 v6, v6, v8, v5
	ds_write_b16 v6, v4 offset:37120
	ds_read2_b32 v[4:5], v7 offset0:7 offset1:8
	s_movk_i32 s1, 0x90
	s_waitcnt lgkmcnt(0)
	v_fma_f32 v57, v2, v4, v69
	v_fmac_f32_e32 v57, v3, v5
	ds_read2_b32 v[4:5], v7 offset0:9 offset1:10
	s_waitcnt lgkmcnt(0)
	v_fmac_f32_e32 v57, v0, v4
	v_fmac_f32_e32 v57, v1, v5
	v_cvt_pk_bf16_f32 v4, v57, v213
	ds_write_b16 v6, v4 offset:37264
	ds_read2_b32 v[4:5], v7 offset0:8 offset1:9
	s_waitcnt lgkmcnt(0)
	v_fma_f32 v58, v2, v4, v69
	v_fmac_f32_e32 v58, v3, v5
	ds_read2_b32 v[4:5], v7 offset0:10 offset1:11
	s_waitcnt lgkmcnt(0)
	v_fmac_f32_e32 v58, v0, v4
	v_fmac_f32_e32 v58, v1, v5
	v_cvt_pk_bf16_f32 v4, v58, v213
	ds_write_b16 v6, v4 offset:37408
	ds_read2_b32 v[4:5], v7 offset0:9 offset1:10
	s_waitcnt lgkmcnt(0)
	v_fma_f32 v59, v2, v4, v69
	v_fmac_f32_e32 v59, v3, v5
	ds_read2_b32 v[4:5], v7 offset0:11 offset1:12
	s_waitcnt lgkmcnt(0)
	v_fmac_f32_e32 v59, v0, v4
	v_fmac_f32_e32 v59, v1, v5
	v_cvt_pk_bf16_f32 v4, v59, v213
	ds_write_b16 v6, v4 offset:37552
	ds_read2_b32 v[4:5], v7 offset0:10 offset1:11
	s_waitcnt lgkmcnt(0)
	v_fma_f32 v60, v2, v4, v69
	v_fmac_f32_e32 v60, v3, v5
	ds_read2_b32 v[4:5], v7 offset0:12 offset1:13
	s_waitcnt lgkmcnt(0)
	v_fmac_f32_e32 v60, v0, v4
	v_fmac_f32_e32 v60, v1, v5
	v_cvt_pk_bf16_f32 v4, v60, v213
	ds_write_b16 v6, v4 offset:37696
	ds_read2_b32 v[4:5], v7 offset0:11 offset1:12
	s_waitcnt lgkmcnt(0)
	v_fma_f32 v61, v2, v4, v69
	v_fmac_f32_e32 v61, v3, v5
	ds_read2_b32 v[4:5], v7 offset0:13 offset1:14
	s_waitcnt lgkmcnt(0)
	v_fmac_f32_e32 v61, v0, v4
	v_fmac_f32_e32 v61, v1, v5
	v_cvt_pk_bf16_f32 v4, v61, v213
	ds_write_b16 v6, v4 offset:37840
	ds_read2_b32 v[4:5], v7 offset0:12 offset1:13
	s_waitcnt lgkmcnt(0)
	v_fma_f32 v62, v2, v4, v69
	v_fmac_f32_e32 v62, v3, v5
	ds_read2_b32 v[4:5], v7 offset0:14 offset1:15
	s_waitcnt lgkmcnt(0)
	v_fmac_f32_e32 v62, v0, v4
	v_fmac_f32_e32 v62, v1, v5
	v_cvt_pk_bf16_f32 v4, v62, v213
	ds_write_b16 v6, v4 offset:37984
	ds_read2_b32 v[4:5], v7 offset0:13 offset1:14
	s_waitcnt lgkmcnt(0)
	v_fma_f32 v63, v2, v4, v69
	v_fmac_f32_e32 v63, v3, v5
	ds_read2_b32 v[4:5], v7 offset0:15 offset1:16
	s_waitcnt lgkmcnt(0)
	v_fmac_f32_e32 v63, v0, v4
	v_fmac_f32_e32 v63, v1, v5
	v_cvt_pk_bf16_f32 v4, v63, v213
	ds_write_b16 v6, v4 offset:38128
	ds_read2_b32 v[4:5], v7 offset0:14 offset1:15
	s_waitcnt lgkmcnt(0)
	v_fma_f32 v64, v2, v4, v69
	v_fmac_f32_e32 v64, v3, v5
	ds_read2_b32 v[4:5], v7 offset0:16 offset1:17
	s_waitcnt lgkmcnt(0)
	v_fmac_f32_e32 v64, v0, v4
	v_fmac_f32_e32 v64, v1, v5
	v_cvt_pk_bf16_f32 v4, v64, v213
	ds_write_b16 v6, v4 offset:38272
	ds_read2_b32 v[4:5], v7 offset0:15 offset1:16
	s_waitcnt lgkmcnt(0)
	v_fma_f32 v65, v2, v4, v69
	v_fmac_f32_e32 v65, v3, v5
	ds_read2_b32 v[4:5], v7 offset0:17 offset1:18
	s_waitcnt lgkmcnt(0)
	v_fmac_f32_e32 v65, v0, v4
	v_fmac_f32_e32 v65, v1, v5
	v_cvt_pk_bf16_f32 v4, v65, v213
	ds_write_b16 v6, v4 offset:38416
	ds_read2_b32 v[4:5], v7 offset0:16 offset1:17
	s_waitcnt lgkmcnt(0)
	v_fma_f32 v66, v2, v4, v69
	v_fmac_f32_e32 v66, v3, v5
	ds_read2_b32 v[4:5], v7 offset0:18 offset1:19
	s_waitcnt lgkmcnt(0)
; DEVI void lru_item(const Params& p, int l, int item, int pass) {
;     ...
;     for (int tt = 0; tt < 16; ++tt) { const float u = cb + w0 * xr[tt - 2] + w1 * xr[tt - 1] + w2 * xr[tt] + w3 * xr[tt + 1]; uo[tt] = u; ub[(16 * tg + tt) * 72 + e] = f2bf(u); } }
;   if (pass && tid < 128) {
;     const int d = tid >> 6, ee = tid & 63, my = isctx ? tq : 2 + tq;
;     const float2* S = ss + d * 34 * 64 + ee;
;     float h = 0.f;
;     if (d == 0) { for (int j = 0; j < my; ++j) { const float2 sv = S[j * 64]; h = sv.x * h + sv.y; } }
;     else {
;       if (my < 2) { for (int j = 1; j > my; --j) { const float2 sv = S[j * 64]; h = sv.x * h + sv.y; } }
;       else {
;         { const float2 sv = S[1 * 64]; h = sv.x * h + sv.y; }
;         { const float2 sv = S[0 * 64]; h = sv.x * h + sv.y; }
;         for (int j = 33; j > my; --j) { const float2 sv = S[j * 64]; h = sv.x * h + sv.y; }
;       }
;     }
;     hc[tid] = h;
;   }
;   __syncthreads();
;   if (pass) {
;     bf16x8 gv2[2];
; #pragma unroll
;     for (int i = 0; i < 2; ++i) { const int idx = tid + i * NTHREADS, chn = idx >> 4, ck = idx & 15; gv2[i] = *(const bf16x8*)(PT + (size_t)(256 + n * 64 + chn) * T + rowbase + t0 + ck * 8); }
; #pragma unroll
;     for (int i = 0; i < 2; ++i) { const int idx = tid + i * NTHREADS, chn = idx >> 4, ck = idx & 15;
; #pragma unroll
;       for (int q = 0; q < 8; ++q) xs[chn * 145 + 8 + ck * 8 + q] = bf2f((u16)gv2[i][q]); }
;   }
;   const bf16x8 A0 = *(const bf16x8*)(ub + (16 * tg + fr) * 72 + 8 * g), A1 = *(const bf16x8*)(ub + (16 * tg + fr) * 72 + 32 + 8 * g);
;   const u16* WGT = (const u16*)(p.ws + OFF_WGT);
;   float* exw = ex + tg * 16 * 65;
;   float av[2][16], bv[2][16];
; #pragma unroll
;   for (int d = 0; d < 2; ++d) {
;     float pre[2][16];
; #pragma unroll
;     for (int mat = 0; mat < 2; ++mat) {
;       const u16* wb = WGT + (size_t)((((l * 2 + d) * 2 + mat) * 4 + n) * 64) * 64 + 8 * g;
;       f32x4 acc[4];
; #pragma unroll
;       for (int nt = 0; nt < 4; ++nt) {
;         const bf16x8 B0 = *(const bf16x8*)(wb + (16 * nt + fr) * 64), B1 = *(const bf16x8*)(wb + (16 * nt + fr) * 64 + 32);
;         f32x4 z = {0.f, 0.f, 0.f, 0.f};
;         z = mfma16(A0, B0, z); z = mfma16(A1, B1, z); acc[nt] = z;
;       }
;       asm volatile("s_waitcnt lgkmcnt(0)" ::: "memory");
; #pragma unroll
;       for (int nt = 0; nt < 4; ++nt)
; #pragma unroll
	v_fmac_f32_e32 v66, v0, v4
	v_fmac_f32_e32 v66, v1, v5
	v_cvt_pk_bf16_f32 v4, v66, v213
	ds_write_b16 v6, v4 offset:38560
	ds_read2_b32 v[4:5], v7 offset0:17 offset1:18
	s_waitcnt lgkmcnt(0)
	v_fma_f32 v67, v2, v4, v69
	v_fmac_f32_e32 v67, v3, v5
	ds_read2_b32 v[4:5], v7 offset0:19 offset1:20
	s_waitcnt lgkmcnt(0)
	v_fmac_f32_e32 v67, v0, v4
	v_fmac_f32_e32 v67, v1, v5
	v_cvt_pk_bf16_f32 v4, v67, v213
	ds_write_b16 v6, v4 offset:38704
	ds_read2_b32 v[4:5], v7 offset0:18 offset1:19
	s_waitcnt lgkmcnt(0)
	v_fma_f32 v68, v2, v4, v69
	v_fmac_f32_e32 v68, v3, v5
	ds_read2_b32 v[4:5], v7 offset0:20 offset1:21
	s_waitcnt lgkmcnt(0)
	v_fmac_f32_e32 v68, v0, v4
	v_fmac_f32_e32 v68, v1, v5
	v_cvt_pk_bf16_f32 v4, v68, v213
	ds_write_b16 v6, v4 offset:38848
	ds_read2_b32 v[4:5], v7 offset0:19 offset1:20
	s_waitcnt lgkmcnt(0)
	v_fma_f32 v70, v2, v4, v69
	v_fmac_f32_e32 v70, v3, v5
	ds_read2_b32 v[4:5], v7 offset0:21 offset1:22
	s_waitcnt lgkmcnt(0)
	v_fmac_f32_e32 v70, v0, v4
	v_fmac_f32_e32 v70, v1, v5
	v_cvt_pk_bf16_f32 v4, v70, v213
	ds_write_b16 v6, v4 offset:38992
	ds_read2_b32 v[4:5], v7 offset0:20 offset1:21
	s_waitcnt lgkmcnt(0)
	v_fma_f32 v71, v2, v4, v69
	v_fmac_f32_e32 v71, v3, v5
	ds_read2_b32 v[4:5], v7 offset0:22 offset1:23
	s_waitcnt lgkmcnt(0)
	v_fmac_f32_e32 v71, v0, v4
	v_fmac_f32_e32 v71, v1, v5
	v_cvt_pk_bf16_f32 v4, v71, v213
	ds_write_b16 v6, v4 offset:39136
	ds_read2_b32 v[4:5], v7 offset0:21 offset1:22
	s_waitcnt lgkmcnt(0)
	v_fmac_f32_e32 v69, v2, v4
	v_fmac_f32_e32 v69, v3, v5
	ds_read2_b32 v[2:3], v7 offset0:23 offset1:24
	s_waitcnt lgkmcnt(0)
	v_fmac_f32_e32 v69, v0, v2
	v_fmac_f32_e32 v69, v1, v3
	v_cvt_pk_bf16_f32 v0, v69, v213
	ds_write_b16 v6, v0 offset:39280
	v_lshl_or_b32 v0, v52, 4, v10
	v_mul_lo_u32 v0, v0, s1
	s_movk_i32 s1, 0x1040
	v_mul_lo_u32 v8, v52, s1
	v_add_u32_e32 v12, 0, v8
	v_lshl_add_u64 v[8:9], s[4:5], 0, v[212:213]
	v_add3_u32 v0, 0, v0, v212
	v_lshl_add_u64 v[28:29], v[8:9], 0, s[90:91]
	v_lshlrev_b32_e32 v212, 7, v10
	v_lshl_add_u64 v[18:19], v[28:29], 0, v[212:213]
	s_waitcnt lgkmcnt(0)
	s_barrier
	ds_read_b128 v[4:7], v0 offset:37120
	ds_read_b128 v[0:3], v0 offset:37184
	v_lshl_add_u32 v72, v10, 2, v12
	global_load_dwordx4 v[8:11], v[18:19], off
	global_load_dwordx4 v[14:17], v[18:19], off offset:64
	v_lshl_add_u64 v[22:23], v[28:29], 0, v[30:31]
	v_lshl_add_u64 v[26:27], v[28:29], 0, v[32:33]
	v_mad_u32_u24 v13, v82, s0, v72
	s_mov_b64 s[0:1], 0x8000
	v_lshl_add_u32 v12, v55, 2, v12
	v_add_u32_e32 v74, 0xd800, v12
	v_add_u32_e32 v75, 0xda00, v12
	v_add_u32_e32 v76, 0xdc00, v12
	v_add_u32_e32 v77, 0xde00, v12
	v_add_u32_e32 v78, 0xe000, v12
	s_waitcnt vmcnt(1) lgkmcnt(1)
	v_mfma_f32_16x16x32_bf16 v[8:11], v[4:7], v[8:11], 0
	v_add_u32_e32 v79, 0xe200, v12
	v_add_u32_e32 v80, 0xe400, v12
	v_add_u32_e32 v81, 0xe600, v12
	s_waitcnt vmcnt(0) lgkmcnt(0)
	v_mfma_f32_16x16x32_bf16 v[8:11], v[0:3], v[14:17], v[8:11]
	global_load_dwordx4 v[14:17], v[18:19], off offset:2048
	s_nop 0
	global_load_dwordx4 v[18:21], v[18:19], off offset:2112
	s_mov_b64 s[4:5], s[44:45]
	s_mov_b64 s[6:7], s[46:47]
	s_mov_b64 s[8:9], s[48:49]
	s_mov_b64 s[10:11], s[50:51]
	s_waitcnt vmcnt(1)
	v_mfma_f32_16x16x32_bf16 v[14:17], v[4:7], v[14:17], 0
	s_waitcnt vmcnt(0)
	v_mfma_f32_16x16x32_bf16 v[14:17], v[0:3], v[18:21], v[14:17]
	global_load_dwordx4 v[18:21], v[22:23], off
	s_nop 0
	global_load_dwordx4 v[22:25], v[22:23], off offset:64
	s_waitcnt vmcnt(1)
	v_mfma_f32_16x16x32_bf16 v[18:21], v[4:7], v[18:21], 0
	s_waitcnt vmcnt(0)
	v_mfma_f32_16x16x32_bf16 v[18:21], v[0:3], v[22:25], v[18:21]
	global_load_dwordx4 v[22:25], v[26:27], off
	global_load_dwordx4 v[36:39], v[26:27], off offset:64
	v_add_u32_e32 v26, 0xd800, v13
	v_add_u32_e32 v27, 0xdc00, v13
	s_waitcnt lgkmcnt(0)
	ds_write2_b32 v26, v8, v14 offset0:64 offset1:80
	ds_write2_b32 v26, v9, v15 offset0:129 offset1:145
	ds_write2_b32 v26, v10, v16 offset0:194 offset1:210
	s_waitcnt vmcnt(1)
	v_mfma_f32_16x16x32_bf16 v[22:25], v[4:7], v[22:25], 0
	s_waitcnt vmcnt(0)
	v_mfma_f32_16x16x32_bf16 v[22:25], v[0:3], v[36:39], v[22:25]
	ds_write2_b32 v27, v11, v17 offset0:3 offset1:19
	s_nop 6
	ds_write2_b32 v26, v18, v22 offset0:96 offset1:112
	ds_write2_b32 v26, v19, v23 offset0:161 offset1:177
	ds_write2_b32 v26, v20, v24 offset0:226 offset1:242
	ds_write2_b32 v27, v21, v25 offset0:35 offset1:51
	v_lshl_add_u64 v[18:19], v[28:29], 0, s[0:1]
	s_waitcnt lgkmcnt(0)
	v_lshl_add_u64 v[22:23], v[18:19], 0, v[212:213]
	ds_read2_b32 v[48:49], v74 offset0:64 offset1:129
	ds_read2_b32 v[44:45], v75 offset0:66 offset1:131
	ds_read2_b32 v[40:41], v76 offset0:68 offset1:133
	ds_read2_b32 v[24:25], v77 offset0:70 offset1:135
	ds_read2_b32 v[20:21], v78 offset0:72 offset1:137
	ds_read2_b32 v[16:17], v79 offset0:74 offset1:139
	ds_read2_b32 v[10:11], v80 offset0:76 offset1:141
	ds_read2_b32 v[8:9], v81 offset0:78 offset1:143
	global_load_dwordx4 v[12:15], v[22:23], off
	global_load_dwordx4 v[36:39], v[22:23], off offset:64
	s_waitcnt vmcnt(1)
	v_mfma_f32_16x16x32_bf16 v[12:15], v[4:7], v[12:15], 0
	v_lshlrev_b32_e32 v212, 1, v35
	v_lshl_add_u64 v[22:23], v[18:19], 0, v[212:213]
	v_mov_b32_e32 v35, v213
	s_waitcnt vmcnt(0)
	v_mfma_f32_16x16x32_bf16 v[12:15], v[0:3], v[36:39], v[12:15]
	global_load_dwordx4 v[36:39], v[22:23], off
	global_load_dwordx4 v[84:87], v[22:23], off offset:64
	v_lshl_add_u64 v[22:23], v[18:19], 0, v[30:31]
	v_lshl_add_u64 v[18:19], v[18:19], 0, v[32:33]
	s_waitcnt vmcnt(1)
	v_mfma_f32_16x16x32_bf16 v[36:39], v[4:7], v[36:39], 0
	s_mov_b32 s0, 0x3cf5c28f
	s_waitcnt vmcnt(0)
	v_mfma_f32_16x16x32_bf16 v[36:39], v[0:3], v[84:87], v[36:39]
	global_load_dwordx4 v[84:87], v[22:23], off
	global_load_dwordx4 v[88:91], v[22:23], off offset:64
	s_waitcnt vmcnt(1)
; DEVI float sigmoidf_(float x) { return __builtin_amdgcn_rcpf(1.f + __expf(-x)); }
; DEVI void lru_item(const Params& p, int l, int item, int pass) {
;     ...
;       for (int tt = 0; tt < 16; ++tt) pre[mat][tt] = exw[tt * 65 + lane];
;     }
;     const float ba = p.in[14][(l * 2 + d) * 256 + c], bx = p.in[16][(l * 2 + d) * 256 + c];
;     const float lam = p.in[17][(l * 2 + d) * 256 + c];
;     const float exl = __expf(-lam); const float sp = exl < 0.03f ? exl * (1.f - exl * (0.5f - exl * (0.33333334f - 0.25f * exl))) : __logf(1.f + exl);
;     float Ap = 1.f, Bp = 0.f;
; #pragma unroll
;     for (int q = 0; q < 16; ++q) {
;       const int tt = d == 0 ? q : 15 - q;
;       const float r = sigmoidf_(pre[0][tt] + ba), ig = sigmoidf_(pre[1][tt] + bx);
;       const float la = -8.f * r * sp;
;       const float a = __expf(la);
;       const float om = fmaxf(1.f - a * a, 0.f);
;       const float bb = sqrtf(om) * (ig * uo[tt]);
;       av[d][tt] = a; bv[d][tt] = bb;
;       Bp = a * Bp + bb; Ap *= a;
;     }
	v_mfma_f32_16x16x32_bf16 v[84:87], v[4:7], v[84:87], 0
	s_waitcnt vmcnt(0)
	v_mfma_f32_16x16x32_bf16 v[84:87], v[0:3], v[88:91], v[84:87]
	global_load_dwordx4 v[88:91], v[18:19], off
	global_load_dwordx4 v[92:95], v[18:19], off offset:64
	s_waitcnt lgkmcnt(0)
	s_waitcnt vmcnt(1)
	v_mfma_f32_16x16x32_bf16 v[88:91], v[4:7], v[88:91], 0
	s_waitcnt vmcnt(0)
	v_mfma_f32_16x16x32_bf16 v[88:91], v[0:3], v[92:95], v[88:91]
	ds_write2_b32 v26, v12, v36 offset0:64 offset1:80
	ds_write2_b32 v26, v13, v37 offset0:129 offset1:145
	ds_write2_b32 v26, v14, v38 offset0:194 offset1:210
	ds_write2_b32 v27, v15, v39 offset0:3 offset1:19
	s_nop 3
	ds_write2_b32 v26, v84, v88 offset0:96 offset1:112
	ds_write2_b32 v26, v85, v89 offset0:161 offset1:177
	ds_write2_b32 v26, v86, v90 offset0:226 offset1:242
	ds_write2_b32 v27, v87, v91 offset0:35 offset1:51
	v_lshlrev_b64 v[38:39], 2, v[34:35]
	s_waitcnt lgkmcnt(0)
	v_lshl_add_u64 v[34:35], s[20:21], 0, v[38:39]
	v_lshl_add_u64 v[36:37], s[4:5], 0, v[38:39]
	v_lshl_add_u64 v[38:39], s[6:7], 0, v[38:39]
	ds_read2_b32 v[50:51], v74 offset0:64 offset1:129
	ds_read2_b32 v[46:47], v75 offset0:66 offset1:131
	ds_read2_b32 v[42:43], v76 offset0:68 offset1:133
	ds_read2_b32 v[26:27], v77 offset0:70 offset1:135
	ds_read2_b32 v[22:23], v78 offset0:72 offset1:137
	ds_read2_b32 v[18:19], v79 offset0:74 offset1:139
	ds_read2_b32 v[14:15], v80 offset0:76 offset1:141
	ds_read2_b32 v[12:13], v81 offset0:78 offset1:143
	global_load_dword v83, v[38:39], off
	global_load_dword v31, v[34:35], off
	global_load_dword v33, v[36:37], off
	global_load_dword v140, v[34:35], off offset:1024
	global_load_dword v141, v[36:37], off offset:1024
	global_load_dword v142, v[38:39], off offset:1024
	s_waitcnt vmcnt(2)
	v_mul_f32_e32 v83, 0xbfb8aa3b, v83
	v_exp_f32_e32 v84, v83
	s_nop 0
	v_cmp_ngt_f32_e64 s[6:7], s0, v84
	s_and_saveexec_b64 s[0:1], s[6:7]
	s_xor_b64 s[4:5], exec, s[0:1]
	s_cbranch_execz .LBB0_1296
	v_add_f32_e32 v83, 1.0, v84
	v_cmp_gt_f32_e64 s[6:7], s63, v83
	s_mov_b32 s0, 0x3f317217
	s_nop 0
	v_cndmask_b32_e64 v84, 0, 32, s[6:7]
	v_ldexp_f32 v83, v83, v84
	v_log_f32_e32 v83, v83
	s_nop 0
	v_mul_f32_e32 v84, 0x3f317217, v83
	v_fma_f32 v84, v83, s0, -v84
	v_fmac_f32_e32 v84, 0x3377d1cf, v83
	s_mov_b32 s0, 0x7f800000
	v_fmac_f32_e32 v84, 0x3f317217, v83
	v_cmp_lt_f32_e64 s[8:9], |v83|, s0
	s_nop 1
	v_cndmask_b32_e64 v83, v83, v84, s[8:9]
	v_cndmask_b32_e64 v84, 0, v225, s[6:7]
	v_sub_f32_e32 v83, v83, v84
.LBB0_1296:
	s_andn2_saveexec_b64 s[4:5], s[4:5]
	v_mov_b32_e32 v83, 0x3eaaaaab
	v_fmamk_f32 v83, v84, 0xbe800000, v83
	v_fma_f32 v83, -v84, v83, 0.5
	v_fma_f32 v83, -v84, v83, 1.0
	v_mul_f32_e32 v83, v84, v83
	s_or_b64 exec, exec, s[4:5]
	s_waitcnt vmcnt(1) lgkmcnt(14)
	v_add_f32_e32 v48, v48, v31
	v_mul_f32_e32 v48, 0xbfb8aa3b, v48
	v_exp_f32_e32 v48, v48
	v_add_f32_e32 v49, v49, v31
	v_mul_f32_e32 v49, 0xbfb8aa3b, v49
	v_exp_f32_e32 v49, v49
	v_add_f32_e32 v48, 1.0, v48
	v_rcp_f32_e32 v48, v48
	s_waitcnt vmcnt(0) lgkmcnt(7)
	v_add_f32_e32 v50, v50, v33
	v_add_f32_e32 v49, 1.0, v49
	v_mul_f32_e32 v50, 0xbfb8aa3b, v50
	v_mul_f32_e32 v48, 0xc1000000, v48
	v_mul_f32_e32 v48, v48, v83
	v_mul_f32_e32 v48, 0x3fb8aa3b, v48
	v_exp_f32_e32 v48, v48
	v_rcp_f32_e32 v49, v49
	v_exp_f32_e32 v50, v50
	v_add_f32_e32 v44, v44, v31
	v_fma_f32 v84, -v48, v48, 1.0
	v_max_f32_e32 v84, 0, v84
	v_mul_f32_e32 v49, 0xc1000000, v49
	v_add_f32_e32 v50, 1.0, v50
	v_mul_f32_e32 v49, v49, v83
	v_rcp_f32_e32 v50, v50
	v_mul_f32_e32 v49, 0x3fb8aa3b, v49
	v_exp_f32_e32 v49, v49
	v_mul_f32_e32 v44, 0xbfb8aa3b, v44
	v_mul_f32_e32 v50, v56, v50
	v_exp_f32_e32 v44, v44
	v_sqrt_f32_e32 v84, v84
	s_nop 0
	v_mul_f32_e32 v50, v50, v84
	v_fma_f32 v84, -v49, v49, 1.0
	v_max_f32_e32 v84, 0, v84
	v_add_f32_e32 v44, 1.0, v44
	v_rcp_f32_e32 v44, v44
	v_add_f32_e32 v51, v51, v33
	v_mul_f32_e32 v51, 0xbfb8aa3b, v51
	v_exp_f32_e32 v51, v51
	v_mul_f32_e32 v44, 0xc1000000, v44
	v_mul_f32_e32 v44, v44, v83
	v_mul_f32_e32 v44, 0x3fb8aa3b, v44
	v_add_f32_e32 v51, 1.0, v51
	v_exp_f32_e32 v44, v44
	v_rcp_f32_e32 v51, v51
	v_fmac_f32_e32 v50, 0, v48
	v_add_f32_e32 v45, v45, v31
	v_mul_f32_e32 v50, v49, v50
	v_mul_f32_e32 v48, v48, v49
	v_fma_f32 v49, -v44, v44, 1.0
	v_mul_f32_e32 v45, 0xbfb8aa3b, v45
	v_sqrt_f32_e32 v84, v84
	v_mul_f32_e32 v51, v57, v51
	v_max_f32_e32 v49, 0, v49
	v_exp_f32_e32 v45, v45
	v_fmac_f32_e32 v50, v51, v84
	s_waitcnt lgkmcnt(6)
	v_add_f32_e32 v46, v46, v33
	v_add_f32_e32 v45, 1.0, v45
	v_mul_f32_e32 v46, 0xbfb8aa3b, v46
	v_rcp_f32_e32 v45, v45
	v_exp_f32_e32 v46, v46
	v_mul_f32_e32 v45, 0xc1000000, v45
	v_add_f32_e32 v46, 1.0, v46
	v_mul_f32_e32 v45, v45, v83
	v_rcp_f32_e32 v46, v46
	v_mul_f32_e32 v45, 0x3fb8aa3b, v45
	v_exp_f32_e32 v45, v45
	v_add_f32_e32 v40, v40, v31
	v_mul_f32_e32 v46, v58, v46
	v_sqrt_f32_e32 v49, v49
	v_mul_f32_e32 v50, v44, v50
	v_mul_f32_e32 v40, 0xbfb8aa3b, v40
	v_fmac_f32_e32 v50, v46, v49
	v_add_f32_e32 v46, v47, v33
	v_fma_f32 v47, -v45, v45, 1.0
	v_exp_f32_e32 v40, v40
	v_max_f32_e32 v47, 0, v47
	v_mul_f32_e32 v44, v44, v48
	v_add_f32_e32 v40, 1.0, v40
	v_rcp_f32_e32 v40, v40
	v_mul_f32_e32 v46, 0xbfb8aa3b, v46
	v_exp_f32_e32 v46, v46
	v_mul_f32_e32 v40, 0xc1000000, v40
	v_mul_f32_e32 v40, v40, v83
	v_mul_f32_e32 v40, 0x3fb8aa3b, v40
	v_add_f32_e32 v46, 1.0, v46
	v_exp_f32_e32 v40, v40
	v_rcp_f32_e32 v46, v46
	v_add_f32_e32 v41, v41, v31
	v_mul_f32_e32 v44, v45, v44
	v_sqrt_f32_e32 v47, v47
	v_mul_f32_e32 v48, v45, v50
	v_fma_f32 v45, -v40, v40, 1.0
	v_mul_f32_e32 v41, 0xbfb8aa3b, v41
	v_mul_f32_e32 v46, v59, v46
	v_max_f32_e32 v45, 0, v45
	v_exp_f32_e32 v41, v41
	v_fmac_f32_e32 v48, v46, v47
	s_waitcnt lgkmcnt(5)
; DEVI float sigmoidf_(float x) { return __builtin_amdgcn_rcpf(1.f + __expf(-x)); }
; DEVI void lru_item(const Params& p, int l, int item, int pass) {
;     ...
;     for (int q = 0; q < 16; ++q) {
;       const int tt = d == 0 ? q : 15 - q;
;       const float r = sigmoidf_(pre[0][tt] + ba), ig = sigmoidf_(pre[1][tt] + bx);
;       const float la = -8.f * r * sp;
;       const float a = __expf(la);
;       const float om = fmaxf(1.f - a * a, 0.f);
;       const float bb = sqrtf(om) * (ig * uo[tt]);
;       av[d][tt] = a; bv[d][tt] = bb;
;       Bp = a * Bp + bb; Ap *= a;
;     }
	v_add_f32_e32 v42, v42, v33
	v_add_f32_e32 v41, 1.0, v41
	v_mul_f32_e32 v42, 0xbfb8aa3b, v42
	v_rcp_f32_e32 v41, v41
	v_exp_f32_e32 v42, v42
	v_mul_f32_e32 v41, 0xc1000000, v41
	v_add_f32_e32 v42, 1.0, v42
	v_mul_f32_e32 v41, v41, v83
	v_rcp_f32_e32 v42, v42
	v_mul_f32_e32 v41, 0x3fb8aa3b, v41
	v_exp_f32_e32 v41, v41
	v_add_f32_e32 v24, v24, v31
	v_mul_f32_e32 v42, v60, v42
	v_sqrt_f32_e32 v45, v45
	v_mul_f32_e32 v46, v40, v48
	v_mul_f32_e32 v24, 0xbfb8aa3b, v24
	v_fmac_f32_e32 v46, v42, v45
	v_add_f32_e32 v42, v43, v33
	v_fma_f32 v43, -v41, v41, 1.0
	v_exp_f32_e32 v24, v24
	v_max_f32_e32 v43, 0, v43
	v_mul_f32_e32 v40, v40, v44
	v_add_f32_e32 v24, 1.0, v24
	v_rcp_f32_e32 v24, v24
	v_mul_f32_e32 v42, 0xbfb8aa3b, v42
	v_exp_f32_e32 v42, v42
	v_mul_f32_e32 v24, 0xc1000000, v24
	v_mul_f32_e32 v24, v24, v83
	v_mul_f32_e32 v24, 0x3fb8aa3b, v24
	v_add_f32_e32 v42, 1.0, v42
	v_exp_f32_e32 v24, v24
	v_rcp_f32_e32 v42, v42
	v_add_f32_e32 v25, v25, v31
	v_mul_f32_e32 v40, v41, v40
	v_sqrt_f32_e32 v43, v43
	v_mul_f32_e32 v44, v41, v46
	v_fma_f32 v41, -v24, v24, 1.0
	v_mul_f32_e32 v25, 0xbfb8aa3b, v25
	v_mul_f32_e32 v42, v61, v42
	v_max_f32_e32 v41, 0, v41
	v_exp_f32_e32 v25, v25
	v_fmac_f32_e32 v44, v42, v43
	s_waitcnt lgkmcnt(4)
	v_add_f32_e32 v26, v26, v33
	v_add_f32_e32 v25, 1.0, v25
	v_mul_f32_e32 v26, 0xbfb8aa3b, v26
	v_rcp_f32_e32 v25, v25
	v_exp_f32_e32 v26, v26
	v_mul_f32_e32 v25, 0xc1000000, v25
	v_add_f32_e32 v26, 1.0, v26
	v_mul_f32_e32 v25, v25, v83
	v_rcp_f32_e32 v26, v26
	v_mul_f32_e32 v25, 0x3fb8aa3b, v25
	v_exp_f32_e32 v25, v25
	v_add_f32_e32 v20, v20, v31
	v_mul_f32_e32 v26, v62, v26
	v_sqrt_f32_e32 v41, v41
	v_mul_f32_e32 v42, v24, v44
	v_mul_f32_e32 v20, 0xbfb8aa3b, v20
	v_fmac_f32_e32 v42, v26, v41
	v_add_f32_e32 v26, v27, v33
	v_fma_f32 v27, -v25, v25, 1.0
	v_exp_f32_e32 v20, v20
	v_max_f32_e32 v27, 0, v27
	v_mul_f32_e32 v24, v24, v40
	v_add_f32_e32 v20, 1.0, v20
	v_rcp_f32_e32 v20, v20
	v_mul_f32_e32 v26, 0xbfb8aa3b, v26
	v_exp_f32_e32 v26, v26
	v_mul_f32_e32 v20, 0xc1000000, v20
	v_mul_f32_e32 v20, v20, v83
	v_mul_f32_e32 v20, 0x3fb8aa3b, v20
	v_add_f32_e32 v26, 1.0, v26
	v_exp_f32_e32 v20, v20
	v_rcp_f32_e32 v26, v26
	v_add_f32_e32 v21, v21, v31
	v_mul_f32_e32 v24, v25, v24
	v_sqrt_f32_e32 v27, v27
	v_mul_f32_e32 v40, v25, v42
	v_fma_f32 v25, -v20, v20, 1.0
	v_mul_f32_e32 v21, 0xbfb8aa3b, v21
	v_mul_f32_e32 v26, v63, v26
	v_max_f32_e32 v25, 0, v25
	v_exp_f32_e32 v21, v21
	v_fmac_f32_e32 v40, v26, v27
	s_waitcnt lgkmcnt(3)
	v_add_f32_e32 v22, v22, v33
	v_add_f32_e32 v21, 1.0, v21
	v_mul_f32_e32 v22, 0xbfb8aa3b, v22
	v_rcp_f32_e32 v21, v21
	v_exp_f32_e32 v22, v22
	v_mul_f32_e32 v21, 0xc1000000, v21
	v_add_f32_e32 v22, 1.0, v22
	v_mul_f32_e32 v21, v21, v83
	v_rcp_f32_e32 v22, v22
	v_mul_f32_e32 v21, 0x3fb8aa3b, v21
	v_exp_f32_e32 v21, v21
	v_add_f32_e32 v16, v16, v31
	v_mul_f32_e32 v22, v64, v22
	v_sqrt_f32_e32 v25, v25
	v_mul_f32_e32 v26, v20, v40
	v_mul_f32_e32 v16, 0xbfb8aa3b, v16
	v_fmac_f32_e32 v26, v22, v25
	v_add_f32_e32 v22, v23, v33
	v_fma_f32 v23, -v21, v21, 1.0
	v_exp_f32_e32 v16, v16
	v_max_f32_e32 v23, 0, v23
	v_mul_f32_e32 v20, v20, v24
	v_add_f32_e32 v16, 1.0, v16
	v_rcp_f32_e32 v16, v16
	v_mul_f32_e32 v22, 0xbfb8aa3b, v22
	v_exp_f32_e32 v22, v22
	v_mul_f32_e32 v16, 0xc1000000, v16
	v_mul_f32_e32 v16, v16, v83
	v_mul_f32_e32 v16, 0x3fb8aa3b, v16
	v_add_f32_e32 v22, 1.0, v22
	v_exp_f32_e32 v16, v16
	v_rcp_f32_e32 v22, v22
	v_add_f32_e32 v17, v17, v31
	v_mul_f32_e32 v20, v21, v20
	v_sqrt_f32_e32 v23, v23
	v_mul_f32_e32 v24, v21, v26
	v_fma_f32 v21, -v16, v16, 1.0
	v_mul_f32_e32 v17, 0xbfb8aa3b, v17
	v_mul_f32_e32 v22, v65, v22
	v_max_f32_e32 v21, 0, v21
	v_exp_f32_e32 v17, v17
	v_fmac_f32_e32 v24, v22, v23
	s_waitcnt lgkmcnt(2)
	v_add_f32_e32 v18, v18, v33
	v_add_f32_e32 v17, 1.0, v17
	v_mul_f32_e32 v18, 0xbfb8aa3b, v18
	v_rcp_f32_e32 v17, v17
	v_exp_f32_e32 v18, v18
	v_mul_f32_e32 v17, 0xc1000000, v17
	v_add_f32_e32 v18, 1.0, v18
	v_mul_f32_e32 v17, v17, v83
	v_rcp_f32_e32 v18, v18
	v_mul_f32_e32 v17, 0x3fb8aa3b, v17
	v_exp_f32_e32 v17, v17
	v_add_f32_e32 v10, v10, v31
	v_mul_f32_e32 v18, v66, v18
	v_sqrt_f32_e32 v21, v21
	v_mul_f32_e32 v22, v16, v24
	v_mul_f32_e32 v10, 0xbfb8aa3b, v10
	v_fmac_f32_e32 v22, v18, v21
	v_add_f32_e32 v18, v19, v33
	v_fma_f32 v19, -v17, v17, 1.0
	v_exp_f32_e32 v10, v10
	v_max_f32_e32 v19, 0, v19
	v_mul_f32_e32 v16, v16, v20
	v_add_f32_e32 v10, 1.0, v10
	v_rcp_f32_e32 v10, v10
	v_mul_f32_e32 v18, 0xbfb8aa3b, v18
	v_exp_f32_e32 v18, v18
	v_mul_f32_e32 v10, 0xc1000000, v10
	v_mul_f32_e32 v10, v10, v83
	v_mul_f32_e32 v10, 0x3fb8aa3b, v10
	v_add_f32_e32 v18, 1.0, v18
	v_exp_f32_e32 v10, v10
	v_rcp_f32_e32 v18, v18
	v_add_f32_e32 v11, v11, v31
	v_mul_f32_e32 v16, v17, v16
	v_sqrt_f32_e32 v19, v19
	v_mul_f32_e32 v20, v17, v22
	v_fma_f32 v17, -v10, v10, 1.0
	v_mul_f32_e32 v11, 0xbfb8aa3b, v11
	v_mul_f32_e32 v18, v67, v18
	v_max_f32_e32 v17, 0, v17
	v_exp_f32_e32 v11, v11
	v_fmac_f32_e32 v20, v18, v19
	s_waitcnt lgkmcnt(1)
	v_add_f32_e32 v14, v14, v33
	v_add_f32_e32 v11, 1.0, v11
	v_mul_f32_e32 v14, 0xbfb8aa3b, v14
	v_rcp_f32_e32 v11, v11
	v_exp_f32_e32 v14, v14
	v_mul_f32_e32 v11, 0xc1000000, v11
	v_add_f32_e32 v14, 1.0, v14
	v_mul_f32_e32 v11, v11, v83
	v_rcp_f32_e32 v14, v14
	v_mul_f32_e32 v11, 0x3fb8aa3b, v11
	v_exp_f32_e32 v11, v11
	v_add_f32_e32 v8, v8, v31
	v_mul_f32_e32 v14, v68, v14
	v_sqrt_f32_e32 v17, v17
	v_mul_f32_e32 v18, v10, v20
	v_mul_f32_e32 v8, 0xbfb8aa3b, v8
	v_fmac_f32_e32 v18, v14, v17
	v_add_f32_e32 v14, v15, v33
	v_fma_f32 v15, -v11, v11, 1.0
	v_exp_f32_e32 v8, v8
	v_max_f32_e32 v15, 0, v15
	v_mul_f32_e32 v10, v10, v16
	v_add_f32_e32 v8, 1.0, v8
	v_rcp_f32_e32 v8, v8
	v_mul_f32_e32 v14, 0xbfb8aa3b, v14
	v_exp_f32_e32 v14, v14
	v_mul_f32_e32 v8, 0xc1000000, v8
	v_mul_f32_e32 v8, v8, v83
	v_mul_f32_e32 v8, 0x3fb8aa3b, v8
	v_add_f32_e32 v14, 1.0, v14
	v_exp_f32_e32 v8, v8
	v_rcp_f32_e32 v14, v14
	v_mul_f32_e32 v10, v11, v10
	v_mul_f32_e32 v14, v70, v14
	v_sqrt_f32_e32 v15, v15
	v_mul_f32_e32 v16, v11, v18
	s_waitcnt lgkmcnt(0)
; DEVI float sigmoidf_(float x) { return __builtin_amdgcn_rcpf(1.f + __expf(-x)); }
; DEVI f32x4 mfma16(bf16x8 a, bf16x8 b, f32x4 c) { return __builtin_amdgcn_mfma_f32_16x16x32_bf16(a, b, c, 0, 0, 0); }
; DEVI void lru_item(const Params& p, int l, int item, int pass) {
;     ...
;     for (int mat = 0; mat < 2; ++mat) {
;       const u16* wb = WGT + (size_t)((((l * 2 + d) * 2 + mat) * 4 + n) * 64) * 64 + 8 * g;
;       f32x4 acc[4];
; #pragma unroll
;       for (int nt = 0; nt < 4; ++nt) {
;         const bf16x8 B0 = *(const bf16x8*)(wb + (16 * nt + fr) * 64), B1 = *(const bf16x8*)(wb + (16 * nt + fr) * 64 + 32);
;         f32x4 z = {0.f, 0.f, 0.f, 0.f};
;         z = mfma16(A0, B0, z); z = mfma16(A1, B1, z); acc[nt] = z;
;       }
;       asm volatile("s_waitcnt lgkmcnt(0)" ::: "memory");
; #pragma unroll
;       for (int nt = 0; nt < 4; ++nt)
; #pragma unroll
;         for (int j = 0; j < 4; ++j) exw[(4 * g + j) * 65 + 16 * nt + fr] = acc[nt][j];
;       asm volatile("s_waitcnt lgkmcnt(0)" ::: "memory");
; #pragma unroll
;       for (int tt = 0; tt < 16; ++tt) pre[mat][tt] = exw[tt * 65 + lane];
;     }
;     const float ba = p.in[14][(l * 2 + d) * 256 + c], bx = p.in[16][(l * 2 + d) * 256 + c];
;     const float lam = p.in[17][(l * 2 + d) * 256 + c];
;     const float exl = __expf(-lam); const float sp = exl < 0.03f ? exl * (1.f - exl * (0.5f - exl * (0.33333334f - 0.25f * exl))) : __logf(1.f + exl);
;     ...
;     for (int q = 0; q < 16; ++q) {
;       const int tt = d == 0 ? q : 15 - q;
;       const float r = sigmoidf_(pre[0][tt] + ba), ig = sigmoidf_(pre[1][tt] + bx);
;       const float la = -8.f * r * sp;
;       const float a = __expf(la);
;       const float om = fmaxf(1.f - a * a, 0.f);
;       const float bb = sqrtf(om) * (ig * uo[tt]);
;       av[d][tt] = a; bv[d][tt] = bb;
;       Bp = a * Bp + bb; Ap *= a;
;     }
;     sm[((d * 8 + tg) * 64 + e) * 2 + 0] = Ap; sm[((d * 8 + tg) * 64 + e) * 2 + 1] = Bp;
	v_add_f32_e32 v11, v12, v33
	v_fma_f32 v12, -v8, v8, 1.0
	v_max_f32_e32 v12, 0, v12
	v_fmac_f32_e32 v16, v14, v15
	v_add_f32_e32 v9, v9, v31
	v_mul_f32_e32 v9, 0xbfb8aa3b, v9
	v_exp_f32_e32 v9, v9
	v_mul_f32_e32 v11, 0xbfb8aa3b, v11
	v_exp_f32_e32 v11, v11
	v_add_f32_e32 v9, 1.0, v9
	v_rcp_f32_e32 v9, v9
	v_add_f32_e32 v11, 1.0, v11
	v_rcp_f32_e32 v11, v11
	v_mul_f32_e32 v9, 0xc1000000, v9
	v_mul_f32_e32 v9, v9, v83
	v_mul_f32_e32 v11, v71, v11
	v_mul_f32_e32 v9, 0x3fb8aa3b, v9
	v_sqrt_f32_e32 v12, v12
	v_mul_f32_e32 v14, v8, v16
	v_fmac_f32_e32 v14, v11, v12
	v_exp_f32_e32 v11, v9
	v_mul_f32_e32 v8, v8, v10
	v_add_f32_e32 v10, v13, v33
	v_mul_f32_e32 v10, 0xbfb8aa3b, v10
	v_fma_f32 v9, -v11, v11, 1.0
	v_max_f32_e32 v9, 0, v9
	v_exp_f32_e32 v10, v10
	s_mov_b64 s[0:1], 0x10000
	v_add_f32_e32 v10, 1.0, v10
	v_rcp_f32_e32 v10, v10
	s_nop 0
	v_mul_f32_e32 v10, v69, v10
	v_mul_f32_e32 v8, v11, v8
	v_lshl_add_u64 v[24:25], v[28:29], 0, s[0:1]
	v_lshlrev_b32_e32 v40, 1, v73
	v_mov_b32_e32 v41, v213
	v_sqrt_f32_e32 v12, v9
	v_mul_f32_e32 v9, v11, v14
	v_fmac_f32_e32 v9, v10, v12
	v_lshlrev_b32_e32 v10, 3, v54
	v_add_u32_e32 v44, 0, v10
	v_add_u32_e32 v10, 0x15b00, v44
	ds_write_b64 v10, v[8:9]
	v_lshl_add_u64 v[12:13], v[24:25], 0, v[40:41]
	global_load_dwordx4 v[8:11], v[12:13], off
	s_nop 0
	global_load_dwordx4 v[12:15], v[12:13], off offset:64
	s_waitcnt vmcnt(1)
	v_mfma_f32_16x16x32_bf16 v[8:11], v[4:7], v[8:11], 0
	v_lshl_add_u64 v[16:17], v[24:25], 0, v[212:213]
	v_mov_b32_e32 v31, v213
	v_lshl_add_u64 v[20:21], v[24:25], 0, v[30:31]
	s_waitcnt vmcnt(0)
	v_mfma_f32_16x16x32_bf16 v[8:11], v[0:3], v[12:15], v[8:11]
	global_load_dwordx4 v[12:15], v[16:17], off
	s_nop 0
	global_load_dwordx4 v[16:19], v[16:17], off offset:64
	v_mov_b32_e32 v33, v213
	v_lshl_add_u64 v[24:25], v[24:25], 0, v[32:33]
	s_waitcnt vmcnt(1)
	v_mfma_f32_16x16x32_bf16 v[12:15], v[4:7], v[12:15], 0
	v_mul_u32_u24_e32 v82, 0x410, v82
	s_mov_b64 s[0:1], 0x18000
	s_waitcnt vmcnt(0)
	v_mfma_f32_16x16x32_bf16 v[12:15], v[0:3], v[16:19], v[12:15]
	global_load_dwordx4 v[16:19], v[20:21], off
	s_nop 0
	global_load_dwordx4 v[20:23], v[20:21], off offset:64
	s_waitcnt vmcnt(1)
	v_mfma_f32_16x16x32_bf16 v[16:19], v[4:7], v[16:19], 0
	s_waitcnt vmcnt(0)
	v_mfma_f32_16x16x32_bf16 v[16:19], v[0:3], v[20:23], v[16:19]
	global_load_dwordx4 v[20:23], v[24:25], off
	s_nop 0
	global_load_dwordx4 v[24:27], v[24:25], off offset:64
	s_waitcnt lgkmcnt(0)
	s_waitcnt vmcnt(1)
	v_mfma_f32_16x16x32_bf16 v[20:23], v[4:7], v[20:23], 0
	s_waitcnt vmcnt(0)
	v_mfma_f32_16x16x32_bf16 v[20:23], v[0:3], v[24:27], v[20:23]
	v_add_u32_e32 v24, v72, v82
	v_add_u32_e32 v45, 0xd800, v24
	v_add_u32_e32 v50, 0xdc00, v24
	ds_write2_b32 v45, v8, v12 offset0:64 offset1:80
	ds_write2_b32 v45, v9, v13 offset0:129 offset1:145
	ds_write2_b32 v45, v10, v14 offset0:194 offset1:210
	ds_write2_b32 v50, v11, v15 offset0:3 offset1:19
	s_nop 0
	ds_write2_b32 v45, v16, v20 offset0:96 offset1:112
	ds_write2_b32 v45, v17, v21 offset0:161 offset1:177
	ds_write2_b32 v45, v18, v22 offset0:226 offset1:242
	ds_write2_b32 v50, v19, v23 offset0:35 offset1:51
	v_lshl_add_u64 v[18:19], v[28:29], 0, s[0:1]
	s_waitcnt lgkmcnt(0)
	v_lshl_add_u64 v[22:23], v[18:19], 0, v[40:41]
	ds_read2_b32 v[8:9], v74 offset0:64 offset1:129
	ds_read2_b32 v[10:11], v75 offset0:66 offset1:131
	ds_read2_b32 v[12:13], v76 offset0:68 offset1:133
	ds_read2_b32 v[14:15], v77 offset0:70 offset1:135
	ds_read2_b32 v[16:17], v78 offset0:72 offset1:137
	ds_read2_b32 v[20:21], v79 offset0:74 offset1:139
	ds_read2_b32 v[24:25], v80 offset0:76 offset1:141
	ds_read2_b32 v[42:43], v81 offset0:78 offset1:143
	global_load_dwordx4 v[26:29], v[22:23], off
	global_load_dwordx4 v[46:49], v[22:23], off offset:64
	s_waitcnt vmcnt(1)
	v_mfma_f32_16x16x32_bf16 v[26:29], v[4:7], v[26:29], 0
	v_lshl_add_u64 v[22:23], v[18:19], 0, v[212:213]
	s_mov_b32 s0, 0x3cf5c28f
	s_waitcnt vmcnt(0)
	v_mfma_f32_16x16x32_bf16 v[26:29], v[0:3], v[46:49], v[26:29]
	global_load_dwordx4 v[46:49], v[22:23], off
	global_load_dwordx4 v[82:85], v[22:23], off offset:64
	v_lshl_add_u64 v[22:23], v[18:19], 0, v[30:31]
	v_lshl_add_u64 v[18:19], v[18:19], 0, v[32:33]
	s_waitcnt vmcnt(1)
	v_mfma_f32_16x16x32_bf16 v[46:49], v[4:7], v[46:49], 0
	s_waitcnt vmcnt(0)
	v_mfma_f32_16x16x32_bf16 v[46:49], v[0:3], v[82:85], v[46:49]
	global_load_dwordx4 v[82:85], v[22:23], off
	global_load_dwordx4 v[86:89], v[22:23], off offset:64
	s_waitcnt vmcnt(1)
	v_mfma_f32_16x16x32_bf16 v[82:85], v[4:7], v[82:85], 0
	s_waitcnt vmcnt(0)
	v_mfma_f32_16x16x32_bf16 v[82:85], v[0:3], v[86:89], v[82:85]
	global_load_dwordx4 v[30:33], v[18:19], off
	global_load_dwordx4 v[86:89], v[18:19], off offset:64
	s_waitcnt lgkmcnt(0)
	s_waitcnt vmcnt(1)
	v_mfma_f32_16x16x32_bf16 v[4:7], v[4:7], v[30:33], 0
	s_waitcnt vmcnt(0)
	v_mfma_f32_16x16x32_bf16 v[0:3], v[0:3], v[86:89], v[4:7]
	ds_write2_b32 v45, v26, v46 offset0:64 offset1:80
	ds_write2_b32 v45, v27, v47 offset0:129 offset1:145
	ds_write2_b32 v45, v28, v48 offset0:194 offset1:210
	ds_write2_b32 v50, v29, v49 offset0:3 offset1:19
	s_nop 3
	ds_write2_b32 v45, v82, v0 offset0:96 offset1:112
	ds_write2_b32 v45, v83, v1 offset0:161 offset1:177
	ds_write2_b32 v45, v84, v2 offset0:226 offset1:242
	ds_write2_b32 v50, v85, v3 offset0:35 offset1:51
	s_waitcnt lgkmcnt(0)
	ds_read2_b32 v[0:1], v74 offset0:64 offset1:129
	ds_read2_b32 v[2:3], v75 offset0:66 offset1:131
	ds_read2_b32 v[4:5], v76 offset0:68 offset1:133
	ds_read2_b32 v[6:7], v77 offset0:70 offset1:135
	ds_read2_b32 v[18:19], v78 offset0:72 offset1:137
	ds_read2_b32 v[22:23], v79 offset0:74 offset1:139
	ds_read2_b32 v[26:27], v80 offset0:76 offset1:141
	ds_read2_b32 v[28:29], v81 offset0:78 offset1:143
	s_waitcnt vmcnt(0)
	v_mov_b32_e32 v31, v140
	v_mov_b32_e32 v30, v141
	v_mov_b32_e32 v32, v142
	s_waitcnt vmcnt(0)
	v_mul_f32_e32 v32, 0xbfb8aa3b, v32
	v_exp_f32_e32 v33, v32
	s_nop 0
	v_cmp_ngt_f32_e64 s[6:7], s0, v33
	s_and_saveexec_b64 s[0:1], s[6:7]
	s_xor_b64 s[4:5], exec, s[0:1]
	s_cbranch_execz .LBB0_1300
	v_add_f32_e32 v32, 1.0, v33
	v_cmp_gt_f32_e64 s[6:7], s63, v32
	s_mov_b32 s0, 0x3f317217
	s_nop 0
	v_cndmask_b32_e64 v33, 0, 32, s[6:7]
	v_ldexp_f32 v32, v32, v33
	v_log_f32_e32 v32, v32
	s_nop 0
	v_mul_f32_e32 v33, 0x3f317217, v32
	v_fma_f32 v33, v32, s0, -v33
	v_fmac_f32_e32 v33, 0x3377d1cf, v32
	s_mov_b32 s0, 0x7f800000
	v_fmac_f32_e32 v33, 0x3f317217, v32
	v_cmp_lt_f32_e64 s[8:9], |v32|, s0
	s_nop 1
	v_cndmask_b32_e64 v32, v32, v33, s[8:9]
	v_cndmask_b32_e64 v33, 0, v225, s[6:7]
	v_sub_f32_e32 v32, v32, v33

; DEVI float bf2f(u16 h) { return __uint_as_float(((unsigned)h) << 16); }
; DEVI f32x4 mfma16(bf16x8 a, bf16x8 b, f32x4 c) { return __builtin_amdgcn_mfma_f32_16x16x32_bf16(a, b, c, 0, 0, 0); }
; DEVI void lru_item(const Params& p, int l, int item, int pass) {
;     ...
;   if (pass) {
;     bf16x8 gv2[2];
; #pragma unroll
;     for (int i = 0; i < 2; ++i) { const int idx = tid + i * NTHREADS, chn = idx >> 4, ck = idx & 15; gv2[i] = *(const bf16x8*)(PT + (size_t)(256 + n * 64 + chn) * T + rowbase + t0 + ck * 8); }
; #pragma unroll
;     for (int i = 0; i < 2; ++i) { const int idx = tid + i * NTHREADS, chn = idx >> 4, ck = idx & 15;
; #pragma unroll
;       for (int q = 0; q < 8; ++q) xs[chn * 145 + 8 + ck * 8 + q] = bf2f((u16)gv2[i][q]); }
;   }
;   const bf16x8 A0 = *(const bf16x8*)(ub + (16 * tg + fr) * 72 + 8 * g), A1 = *(const bf16x8*)(ub + (16 * tg + fr) * 72 + 32 + 8 * g);
;   const u16* WGT = (const u16*)(p.ws + OFF_WGT);
;   float* exw = ex + tg * 16 * 65;
;   float av[2][16], bv[2][16];
; #pragma unroll
;   for (int d = 0; d < 2; ++d) {
;     float pre[2][16];
; #pragma unroll
;     for (int mat = 0; mat < 2; ++mat) {
;       const u16* wb = WGT + (size_t)((((l * 2 + d) * 2 + mat) * 4 + n) * 64) * 64 + 8 * g;
;       f32x4 acc[4];
; #pragma unroll
;       for (int nt = 0; nt < 4; ++nt) {
;         const bf16x8 B0 = *(const bf16x8*)(wb + (16 * nt + fr) * 64), B1 = *(const bf16x8*)(wb + (16 * nt + fr) * 64 + 32);
;         f32x4 z = {0.f, 0.f, 0.f, 0.f};
;         z = mfma16(A0, B0, z); z = mfma16(A1, B1, z); acc[nt] = z;
;       }
;       asm volatile("s_waitcnt lgkmcnt(0)" ::: "memory");
; #pragma unroll
;       for (int nt = 0; nt < 4; ++nt)
; #pragma unroll
;         for (int j = 0; j < 4; ++j) exw[(4 * g + j) * 65 + 16 * nt + fr] = acc[nt][j];
;       asm volatile("s_waitcnt lgkmcnt(0)" ::: "memory");
; #pragma unroll
;       for (int tt = 0; tt < 16; ++tt) pre[mat][tt] = exw[tt * 65 + lane];
.LBB0_1555:
	s_or_b64 exec, exec, s[6:7]
	s_bitset1_b32 s1, 8
	s_lshl_b32 s5, s76, 1
	v_lshlrev_b32_e32 v0, 3, v18
	s_add_u32 s6, s36, s5
	v_and_b32_e32 v8, 0x78, v0
	s_addc_u32 s7, s37, 0
	v_lshlrev_b32_e32 v212, 1, v8
	v_ashrrev_i32_e32 v9, 4, v76
	v_lshl_add_u64 v[4:5], s[6:7], 0, v[212:213]
	v_add_u32_e32 v0, s1, v9
	v_mad_i64_i32 v[0:1], s[6:7], v0, s87, v[4:5]
	s_waitcnt lgkmcnt(0)
	s_barrier
	global_load_dwordx4 v[0:3], v[0:1], off
	v_ashrrev_i32_e32 v11, 4, v19
	v_add_u32_e32 v6, s1, v11
	v_mad_i64_i32 v[4:5], s[6:7], v6, s87, v[4:5]
	global_load_dwordx4 v[4:7], v[4:5], off
	s_movk_i32 s1, 0x244
	v_mul_lo_u32 v9, v9, s1
	v_lshlrev_b32_e32 v8, 2, v8
	v_add3_u32 v9, 0, v9, v8
	v_lshlrev_b32_e32 v61, 4, v56
	v_and_b32_e32 v10, 15, v18
	v_readlane_b32 s6, v252, 63
	v_and_b32_e32 v212, 48, v57
	v_readlane_b32 s7, v253, 0
	s_lshl_b32 s0, s0, 13
	s_or_b32 s90, s0, s89
	v_lshlrev_b32_e32 v107, 6, v10
	v_mov_b32_e32 v31, v213
	v_mov_b32_e32 v33, v213
	v_lshrrev_b32_e32 v75, 4, v57
	s_movk_i32 s0, 0x410
	v_or_b32_e32 v35, 0x400, v107
	v_or_b32_e32 v36, s88, v55
	v_mov_b32_e32 v37, v213
	v_readlane_b32 s8, v252, 30
	v_readlane_b32 s9, v252, 31
	v_readlane_b32 s10, v252, 32
	v_readlane_b32 s11, v252, 33
	v_readlane_b32 s12, v252, 34
	v_readlane_b32 s13, v252, 35
	v_readlane_b32 s14, v252, 36
	v_readlane_b32 s15, v252, 37
	v_readlane_b32 s16, v252, 38
	v_readlane_b32 s17, v252, 39
	v_readlane_b32 s18, v252, 40
	v_readlane_b32 s19, v252, 41
	v_readlane_b32 s20, v252, 42
	v_readlane_b32 s21, v252, 43
	v_readlane_b32 s22, v252, 44
	v_readlane_b32 s23, v252, 45
	s_waitcnt vmcnt(1)
	v_and_b32_e32 v12, 0xffff0000, v0
	v_lshlrev_b32_e32 v0, 16, v0
	ds_write2_b32 v9, v0, v12 offset0:8 offset1:9
	v_and_b32_e32 v0, 0xffff0000, v1
	v_lshlrev_b32_e32 v1, 16, v1
	ds_write2_b32 v9, v1, v0 offset0:10 offset1:11
	v_and_b32_e32 v0, 0xffff0000, v2
	v_lshlrev_b32_e32 v1, 16, v2
	ds_write2_b32 v9, v1, v0 offset0:12 offset1:13
	v_and_b32_e32 v0, 0xffff0000, v3
	v_lshlrev_b32_e32 v1, 16, v3
	ds_write2_b32 v9, v1, v0 offset0:14 offset1:15
	v_mul_lo_u32 v0, v11, s1
	v_add3_u32 v0, 0, v0, v8
	s_waitcnt vmcnt(0)
	v_and_b32_e32 v1, 0xffff0000, v4
	v_lshlrev_b32_e32 v2, 16, v4
	ds_write2_b32 v0, v2, v1 offset0:8 offset1:9
	v_and_b32_e32 v1, 0xffff0000, v5
	v_lshlrev_b32_e32 v2, 16, v5
	ds_write2_b32 v0, v2, v1 offset0:10 offset1:11
	v_and_b32_e32 v1, 0xffff0000, v6
	v_lshlrev_b32_e32 v2, 16, v6
	ds_write2_b32 v0, v2, v1 offset0:12 offset1:13
	v_and_b32_e32 v1, 0xffff0000, v7
	v_lshlrev_b32_e32 v2, 16, v7
	ds_write2_b32 v0, v2, v1 offset0:14 offset1:15
	v_or_b32_e32 v0, v61, v10
	s_movk_i32 s1, 0x90
	v_mul_lo_u32 v0, v0, s1
	s_movk_i32 s1, 0x1040
	v_mul_lo_u32 v8, v56, s1
	v_add_u32_e32 v11, 0, v8
	v_lshl_add_u64 v[8:9], s[6:7], 0, v[212:213]
	v_add3_u32 v0, 0, v0, v212
	v_lshl_add_u64 v[28:29], v[8:9], 0, s[90:91]
	v_lshlrev_b32_e32 v212, 7, v10
	v_lshl_add_u64 v[16:17], v[28:29], 0, v[212:213]
	ds_read_b128 v[4:7], v0 offset:37120
	ds_read_b128 v[0:3], v0 offset:37184
	v_lshl_add_u32 v90, v10, 2, v11
	v_lshl_add_u32 v34, v57, 2, v11
	global_load_dwordx4 v[8:11], v[16:17], off
	global_load_dwordx4 v[12:15], v[16:17], off offset:64
	v_add_u32_e32 v97, 0xd800, v34
	v_add_u32_e32 v98, 0xda00, v34
	v_add_u32_e32 v99, 0xdc00, v34
	v_add_u32_e32 v100, 0xde00, v34
	v_add_u32_e32 v102, 0xe000, v34
	v_add_u32_e32 v103, 0xe200, v34
	v_add_u32_e32 v104, 0xe400, v34
	v_add_u32_e32 v105, 0xe600, v34
	v_lshlrev_b32_e32 v34, 1, v35
	v_mov_b32_e32 v35, v213
	s_waitcnt vmcnt(1) lgkmcnt(1)
	v_mfma_f32_16x16x32_bf16 v[8:11], v[4:7], v[8:11], 0
	s_waitcnt vmcnt(0) lgkmcnt(0)
	v_mfma_f32_16x16x32_bf16 v[8:11], v[0:3], v[12:15], v[8:11]
	global_load_dwordx4 v[12:15], v[16:17], off offset:2048
	s_nop 0
	global_load_dwordx4 v[16:19], v[16:17], off offset:2112
	s_waitcnt vmcnt(1)
	v_mfma_f32_16x16x32_bf16 v[12:15], v[4:7], v[12:15], 0
	s_waitcnt vmcnt(0)
	v_mfma_f32_16x16x32_bf16 v[12:15], v[0:3], v[16:19], v[12:15]
	v_or_b32_e32 v16, 0x800, v107
	v_lshlrev_b32_e32 v30, 1, v16
	v_lshl_add_u64 v[20:21], v[28:29], 0, v[30:31]
	global_load_dwordx4 v[16:19], v[20:21], off
	s_nop 0
	global_load_dwordx4 v[20:23], v[20:21], off offset:64
	s_waitcnt vmcnt(1)
	v_mfma_f32_16x16x32_bf16 v[16:19], v[4:7], v[16:19], 0
	s_waitcnt vmcnt(0)
	v_mfma_f32_16x16x32_bf16 v[16:19], v[0:3], v[20:23], v[16:19]
	v_or_b32_e32 v20, 0xc00, v107
	v_lshlrev_b32_e32 v32, 1, v20
	v_lshl_add_u64 v[24:25], v[28:29], 0, v[32:33]
	global_load_dwordx4 v[20:23], v[24:25], off
	s_nop 0
	global_load_dwordx4 v[24:27], v[24:25], off offset:64
	s_waitcnt lgkmcnt(0)
	s_waitcnt vmcnt(1)
	v_mfma_f32_16x16x32_bf16 v[20:23], v[4:7], v[20:23], 0
	s_waitcnt vmcnt(0)
	v_mfma_f32_16x16x32_bf16 v[20:23], v[0:3], v[24:27], v[20:23]
	v_mad_u32_u24 v24, v75, s0, v90
	v_add_u32_e32 v26, 0xd800, v24
	v_add_u32_e32 v27, 0xdc00, v24
	s_mov_b64 s[0:1], 0x8000
	ds_write2_b32 v26, v8, v12 offset0:64 offset1:80
	ds_write2_b32 v26, v9, v13 offset0:129 offset1:145
	ds_write2_b32 v26, v10, v14 offset0:194 offset1:210
	ds_write2_b32 v27, v11, v15 offset0:3 offset1:19
	ds_write2_b32 v26, v16, v20 offset0:96 offset1:112
	ds_write2_b32 v26, v17, v21 offset0:161 offset1:177
	ds_write2_b32 v26, v18, v22 offset0:226 offset1:242
	ds_write2_b32 v27, v19, v23 offset0:35 offset1:51
	v_lshl_add_u64 v[18:19], v[28:29], 0, s[0:1]
	s_waitcnt lgkmcnt(0)
; DEVI float sigmoidf_(float x) { return __builtin_amdgcn_rcpf(1.f + __expf(-x)); }
; DEVI void lru_item(const Params& p, int l, int item, int pass) {
;     ...
;       for (int tt = 0; tt < 16; ++tt) pre[mat][tt] = exw[tt * 65 + lane];
;     }
;     const float ba = p.in[14][(l * 2 + d) * 256 + c], bx = p.in[16][(l * 2 + d) * 256 + c];
;     const float lam = p.in[17][(l * 2 + d) * 256 + c];
;     const float exl = __expf(-lam); const float sp = exl < 0.03f ? exl * (1.f - exl * (0.5f - exl * (0.33333334f - 0.25f * exl))) : __logf(1.f + exl);
;     float Ap = 1.f, Bp = 0.f;
; #pragma unroll
;     for (int q = 0; q < 16; ++q) {
;       const int tt = d == 0 ? q : 15 - q;
;       const float r = sigmoidf_(pre[0][tt] + ba), ig = sigmoidf_(pre[1][tt] + bx);
;       const float la = -8.f * r * sp;
;       const float a = __expf(la);
;       const float om = fmaxf(1.f - a * a, 0.f);
;       const float bb = sqrtf(om) * (ig * uo[tt]);
;       av[d][tt] = a; bv[d][tt] = bb;
;       Bp = a * Bp + bb; Ap *= a;
;     }
	v_lshl_add_u64 v[22:23], v[18:19], 0, v[212:213]
	ds_read2_b32 v[50:51], v97 offset0:64 offset1:129
	ds_read2_b32 v[46:47], v98 offset0:66 offset1:131
	ds_read2_b32 v[42:43], v99 offset0:68 offset1:133
	ds_read2_b32 v[24:25], v100 offset0:70 offset1:135
	ds_read2_b32 v[20:21], v102 offset0:72 offset1:137
	ds_read2_b32 v[16:17], v103 offset0:74 offset1:139
	ds_read2_b32 v[10:11], v104 offset0:76 offset1:141
	ds_read2_b32 v[8:9], v105 offset0:78 offset1:143
	global_load_dwordx4 v[12:15], v[22:23], off
	global_load_dwordx4 v[38:41], v[22:23], off offset:64
	v_lshl_add_u64 v[22:23], v[18:19], 0, v[34:35]
	s_mov_b32 s0, 0x3cf5c28f
	s_waitcnt vmcnt(1)
	v_mfma_f32_16x16x32_bf16 v[12:15], v[4:7], v[12:15], 0
	s_waitcnt vmcnt(0)
	v_mfma_f32_16x16x32_bf16 v[12:15], v[0:3], v[38:41], v[12:15]
	global_load_dwordx4 v[38:41], v[22:23], off
	global_load_dwordx4 v[78:81], v[22:23], off offset:64
	v_lshl_add_u64 v[22:23], v[18:19], 0, v[30:31]
	v_lshl_add_u64 v[18:19], v[18:19], 0, v[32:33]
	s_waitcnt vmcnt(1)
	v_mfma_f32_16x16x32_bf16 v[38:41], v[4:7], v[38:41], 0
	s_waitcnt vmcnt(0)
	v_mfma_f32_16x16x32_bf16 v[38:41], v[0:3], v[78:81], v[38:41]
	global_load_dwordx4 v[78:81], v[22:23], off
	global_load_dwordx4 v[82:85], v[22:23], off offset:64
	s_waitcnt vmcnt(1)
	v_mfma_f32_16x16x32_bf16 v[78:81], v[4:7], v[78:81], 0
	s_waitcnt vmcnt(0)
	v_mfma_f32_16x16x32_bf16 v[78:81], v[0:3], v[82:85], v[78:81]
	global_load_dwordx4 v[82:85], v[18:19], off
	global_load_dwordx4 v[86:89], v[18:19], off offset:64
	s_waitcnt lgkmcnt(0)
	s_waitcnt vmcnt(1)
	v_mfma_f32_16x16x32_bf16 v[82:85], v[4:7], v[82:85], 0
	s_waitcnt vmcnt(0)
	v_mfma_f32_16x16x32_bf16 v[82:85], v[0:3], v[86:89], v[82:85]
	ds_write2_b32 v26, v12, v38 offset0:64 offset1:80
	ds_write2_b32 v26, v13, v39 offset0:129 offset1:145
	ds_write2_b32 v26, v14, v40 offset0:194 offset1:210
	ds_write2_b32 v27, v15, v41 offset0:3 offset1:19
	s_nop 3
	ds_write2_b32 v26, v78, v82 offset0:96 offset1:112
	ds_write2_b32 v26, v79, v83 offset0:161 offset1:177
	ds_write2_b32 v26, v80, v84 offset0:226 offset1:242
	ds_write2_b32 v27, v81, v85 offset0:35 offset1:51
	v_lshlrev_b64 v[40:41], 2, v[36:37]
	v_lshl_add_u64 v[36:37], s[20:21], 0, v[40:41]
	v_readlane_b32 s8, v252, 46
	v_readlane_b32 s9, v252, 47
	v_readlane_b32 s10, v252, 48
	v_readlane_b32 s11, v252, 49
	s_waitcnt lgkmcnt(0)
	v_lshl_add_u64 v[38:39], s[8:9], 0, v[40:41]
	ds_read2_b32 v[52:53], v97 offset0:64 offset1:129
	ds_read2_b32 v[48:49], v98 offset0:66 offset1:131
	ds_read2_b32 v[44:45], v99 offset0:68 offset1:133
	ds_read2_b32 v[26:27], v100 offset0:70 offset1:135
	ds_read2_b32 v[22:23], v102 offset0:72 offset1:137
	ds_read2_b32 v[18:19], v103 offset0:74 offset1:139
	ds_read2_b32 v[14:15], v104 offset0:76 offset1:141
	ds_read2_b32 v[12:13], v105 offset0:78 offset1:143
	v_lshl_add_u64 v[40:41], s[10:11], 0, v[40:41]
	global_load_dword v35, v[40:41], off
	global_load_dword v31, v[36:37], off
	global_load_dword v33, v[38:39], off
	global_load_dword v140, v[36:37], off offset:1024
	global_load_dword v141, v[38:39], off offset:1024
	global_load_dword v142, v[40:41], off offset:1024
	v_readlane_b32 s12, v252, 50
	v_readlane_b32 s13, v252, 51
	v_readlane_b32 s14, v252, 52
	v_readlane_b32 s15, v252, 53
	v_readlane_b32 s16, v252, 54
	v_readlane_b32 s17, v252, 55
	v_readlane_b32 s18, v252, 56
	v_readlane_b32 s19, v252, 57
	v_readlane_b32 s20, v252, 58
	v_readlane_b32 s21, v252, 59
	v_readlane_b32 s22, v252, 60
	v_readlane_b32 s23, v252, 61
	s_waitcnt vmcnt(2)
	v_mul_f32_e32 v35, 0xbfb8aa3b, v35
	v_exp_f32_e32 v77, v35
	s_nop 0
	v_cmp_ngt_f32_e32 vcc, s0, v77
	s_and_saveexec_b64 s[0:1], vcc
	s_xor_b64 s[8:9], exec, s[0:1]
	s_cbranch_execz .LBB0_1557
	v_add_f32_e32 v35, 1.0, v77
	v_cmp_gt_f32_e32 vcc, s63, v35
	s_mov_b32 s0, 0x3f317217
	s_nop 0
	v_cndmask_b32_e64 v77, 0, 32, vcc
	v_ldexp_f32 v35, v35, v77
	v_log_f32_e32 v35, v35
	s_nop 0
	v_mul_f32_e32 v77, 0x3f317217, v35
	v_fma_f32 v77, v35, s0, -v77
	v_fmac_f32_e32 v77, 0x3377d1cf, v35
	s_mov_b32 s0, 0x7f800000
	v_fmac_f32_e32 v77, 0x3f317217, v35
	v_cmp_lt_f32_e64 s[6:7], |v35|, s0
	s_nop 1
	v_cndmask_b32_e64 v35, v35, v77, s[6:7]
	v_cndmask_b32_e32 v77, 0, v225, vcc
	v_sub_f32_e32 v35, v35, v77
.LBB0_1557:
	s_andn2_saveexec_b64 s[6:7], s[8:9]
	v_mov_b32_e32 v35, 0x3eaaaaab
	v_fmamk_f32 v35, v77, 0xbe800000, v35
	v_fma_f32 v35, -v77, v35, 0.5
	v_fma_f32 v35, -v77, v35, 1.0
	v_mul_f32_e32 v35, v77, v35
	s_or_b64 exec, exec, s[6:7]
	s_waitcnt vmcnt(1) lgkmcnt(14)
	v_add_f32_e32 v50, v50, v31
	v_mul_f32_e32 v50, 0xbfb8aa3b, v50
	v_exp_f32_e32 v50, v50
	s_waitcnt vmcnt(0) lgkmcnt(7)
	v_add_f32_e32 v52, v52, v33
	v_mul_f32_e32 v52, 0xbfb8aa3b, v52
	v_exp_f32_e32 v52, v52
	v_add_f32_e32 v50, 1.0, v50
	v_rcp_f32_e32 v50, v50
	v_mul_u32_u24_e32 v108, 0x410, v75
	v_add_f32_e32 v52, 1.0, v52
	v_rcp_f32_e32 v75, v52
	v_mul_f32_e32 v50, 0xc1000000, v50
	v_mul_f32_e32 v50, v50, v35
	v_mul_f32_e32 v50, 0x3fb8aa3b, v50
	v_exp_f32_e32 v52, v50
	v_add_f32_e32 v51, v51, v31
	v_mul_f32_e32 v51, 0xbfb8aa3b, v51
	v_exp_f32_e32 v51, v51
	v_fma_f32 v50, -v52, v52, 1.0
	v_max_f32_e32 v50, 0, v50
	v_add_f32_e32 v51, 1.0, v51
	v_rcp_f32_e32 v51, v51
	v_add_f32_e32 v53, v53, v33
	v_mul_f32_e32 v53, 0xbfb8aa3b, v53
	v_exp_f32_e32 v53, v53
	v_mul_f32_e32 v51, 0xc1000000, v51
	v_mul_f32_e32 v51, v51, v35
	v_add_f32_e32 v53, 1.0, v53
	v_mul_f32_e32 v51, 0x3fb8aa3b, v51
	v_sqrt_f32_e32 v50, v50
	v_rcp_f32_e32 v77, v53
	v_exp_f32_e32 v53, v51
	v_add_f32_e32 v46, v46, v31
	v_mul_f32_e32 v46, 0xbfb8aa3b, v46
	v_exp_f32_e32 v46, v46
	v_fma_f32 v51, -v53, v53, 1.0
	v_max_f32_e32 v51, 0, v51
	v_add_f32_e32 v46, 1.0, v46
	v_rcp_f32_e32 v46, v46
	s_waitcnt lgkmcnt(6)
; DEVI float sigmoidf_(float x) { return __builtin_amdgcn_rcpf(1.f + __expf(-x)); }
; DEVI void lru_item(const Params& p, int l, int item, int pass) {
;     ...
;     for (int q = 0; q < 16; ++q) {
;       const int tt = d == 0 ? q : 15 - q;
;       const float r = sigmoidf_(pre[0][tt] + ba), ig = sigmoidf_(pre[1][tt] + bx);
;       const float la = -8.f * r * sp;
;       const float a = __expf(la);
;       const float om = fmaxf(1.f - a * a, 0.f);
;       const float bb = sqrtf(om) * (ig * uo[tt]);
;       av[d][tt] = a; bv[d][tt] = bb;
;       Bp = a * Bp + bb; Ap *= a;
;     }
	v_add_f32_e32 v48, v48, v33
	v_mul_f32_e32 v48, 0xbfb8aa3b, v48
	v_exp_f32_e32 v48, v48
	v_mul_f32_e32 v46, 0xc1000000, v46
	v_mul_f32_e32 v46, v46, v35
	v_add_f32_e32 v48, 1.0, v48
	v_mul_f32_e32 v46, 0x3fb8aa3b, v46
	v_sqrt_f32_e32 v51, v51
	v_rcp_f32_e32 v78, v48
	v_exp_f32_e32 v48, v46
	v_add_f32_e32 v47, v47, v31
	v_mul_f32_e32 v47, 0xbfb8aa3b, v47
	v_exp_f32_e32 v47, v47
	v_fma_f32 v46, -v48, v48, 1.0
	v_max_f32_e32 v46, 0, v46
	v_add_f32_e32 v47, 1.0, v47
	v_rcp_f32_e32 v47, v47
	v_add_f32_e32 v49, v49, v33
	v_mul_f32_e32 v49, 0xbfb8aa3b, v49
	v_exp_f32_e32 v49, v49
	v_mul_f32_e32 v47, 0xc1000000, v47
	v_mul_f32_e32 v47, v47, v35
	v_mul_f32_e32 v78, v60, v78
	v_add_f32_e32 v49, 1.0, v49
	v_sqrt_f32_e32 v46, v46
	v_mul_f32_e32 v47, 0x3fb8aa3b, v47
	v_mul_f32_e32 v46, v78, v46
	v_rcp_f32_e32 v78, v49
	v_exp_f32_e32 v49, v47
	v_add_f32_e32 v42, v42, v31
	v_mul_f32_e32 v42, 0xbfb8aa3b, v42
	v_exp_f32_e32 v42, v42
	v_fma_f32 v47, -v49, v49, 1.0
	v_max_f32_e32 v47, 0, v47
	v_add_f32_e32 v42, 1.0, v42
	v_rcp_f32_e32 v42, v42
	v_mul_f32_e32 v75, v58, v75
	v_mul_f32_e32 v50, v75, v50
	v_mul_f32_e32 v77, v59, v77
	v_fma_f32 v75, 0, v52, v50
	v_mul_f32_e32 v51, v77, v51
	v_mul_f32_e32 v42, 0xc1000000, v42
	v_fma_f32 v75, v53, v75, v51
	v_sqrt_f32_e32 v47, v47
	v_mul_f32_e32 v78, v62, v78
	v_mul_f32_e32 v42, v42, v35
	v_fma_f32 v75, v48, v75, v46
	v_mul_f32_e32 v47, v78, v47
	v_mul_f32_e32 v42, 0x3fb8aa3b, v42
	v_fma_f32 v78, v49, v75, v47
	v_exp_f32_e32 v75, v42
	v_add_f32_e32 v43, v43, v31
	s_waitcnt lgkmcnt(5)
	v_add_f32_e32 v44, v44, v33
	v_mul_f32_e32 v43, 0xbfb8aa3b, v43
	v_fma_f32 v42, -v75, v75, 1.0
	v_max_f32_e32 v42, 0, v42
	v_mul_f32_e32 v44, 0xbfb8aa3b, v44
	v_exp_f32_e32 v43, v43
	v_exp_f32_e32 v44, v44
	v_mul_f32_e32 v77, v52, v53
	v_add_f32_e32 v43, 1.0, v43
	v_add_f32_e32 v44, 1.0, v44
	v_rcp_f32_e32 v43, v43
	v_rcp_f32_e32 v44, v44
	v_mul_f32_e32 v77, v48, v77
	v_mul_f32_e32 v43, 0xc1000000, v43
	v_mul_f32_e32 v44, v63, v44
	v_mul_f32_e32 v43, v43, v35
	v_sqrt_f32_e32 v42, v42
	v_mul_f32_e32 v77, v49, v77
	v_mul_f32_e32 v44, v44, v42
	v_mul_f32_e32 v43, 0x3fb8aa3b, v43
	v_fma_f32 v42, v75, v78, v44
	v_mul_f32_e32 v78, v75, v77
	v_exp_f32_e32 v77, v43
	v_add_f32_e32 v24, v24, v31
	v_mul_f32_e32 v24, 0xbfb8aa3b, v24
	v_exp_f32_e32 v24, v24
	v_fma_f32 v43, -v77, v77, 1.0
	v_max_f32_e32 v43, 0, v43
	v_add_f32_e32 v24, 1.0, v24
	v_rcp_f32_e32 v24, v24
	v_add_f32_e32 v45, v45, v33
	v_mul_f32_e32 v45, 0xbfb8aa3b, v45
	v_exp_f32_e32 v45, v45
	v_mul_f32_e32 v24, 0xc1000000, v24
	v_mul_f32_e32 v24, v24, v35
	v_mul_f32_e32 v24, 0x3fb8aa3b, v24
	v_add_f32_e32 v45, 1.0, v45
	v_sqrt_f32_e32 v43, v43
	v_exp_f32_e32 v79, v24
	v_rcp_f32_e32 v45, v45
	v_add_f32_e32 v25, v25, v31
	v_mul_f32_e32 v25, 0xbfb8aa3b, v25
	v_fma_f32 v24, -v79, v79, 1.0
	v_mul_f32_e32 v45, v64, v45
	v_max_f32_e32 v24, 0, v24
	v_exp_f32_e32 v25, v25
	v_mul_f32_e32 v45, v45, v43
	v_mul_f32_e32 v43, v77, v78
	v_add_f32_e32 v25, 1.0, v25
	s_waitcnt lgkmcnt(4)
	v_add_f32_e32 v26, v26, v33
	v_rcp_f32_e32 v25, v25
	v_mul_f32_e32 v26, 0xbfb8aa3b, v26
	v_exp_f32_e32 v26, v26
	v_mul_f32_e32 v25, 0xc1000000, v25
	v_mul_f32_e32 v25, v25, v35
	v_add_f32_e32 v26, 1.0, v26
	v_mul_f32_e32 v25, 0x3fb8aa3b, v25
	v_rcp_f32_e32 v26, v26
	v_exp_f32_e32 v81, v25
	v_add_f32_e32 v20, v20, v31
	v_mul_f32_e32 v20, 0xbfb8aa3b, v20
	v_exp_f32_e32 v20, v20
	v_mul_f32_e32 v26, v65, v26
	v_sqrt_f32_e32 v24, v24
	v_fma_f32 v25, -v81, v81, 1.0
	v_fma_f32 v42, v77, v42, v45
	v_mul_f32_e32 v78, v26, v24
	v_max_f32_e32 v25, 0, v25
	v_fma_f32 v24, v79, v42, v78
	v_add_f32_e32 v20, 1.0, v20
	v_rcp_f32_e32 v20, v20
	v_add_f32_e32 v27, v27, v33
	v_mul_f32_e32 v27, 0xbfb8aa3b, v27
	v_exp_f32_e32 v27, v27
	v_mul_f32_e32 v26, v79, v43
	v_mul_f32_e32 v20, 0xc1000000, v20
	v_mul_f32_e32 v20, v20, v35
	v_mul_f32_e32 v20, 0x3fb8aa3b, v20
	v_add_f32_e32 v27, 1.0, v27
	v_exp_f32_e32 v83, v20
	v_rcp_f32_e32 v27, v27
	v_add_f32_e32 v21, v21, v31
	v_mul_f32_e32 v21, 0xbfb8aa3b, v21
	v_fma_f32 v20, -v83, v83, 1.0
	v_exp_f32_e32 v21, v21
	v_sqrt_f32_e32 v25, v25
	v_mul_f32_e32 v27, v66, v27
	v_max_f32_e32 v20, 0, v20
	v_mul_f32_e32 v80, v27, v25
	v_mul_f32_e32 v25, v81, v26
	v_add_f32_e32 v21, 1.0, v21
	s_waitcnt lgkmcnt(3)
	v_add_f32_e32 v22, v22, v33
	v_rcp_f32_e32 v21, v21
	v_mul_f32_e32 v22, 0xbfb8aa3b, v22
	v_exp_f32_e32 v22, v22
	v_mul_f32_e32 v21, 0xc1000000, v21
	v_mul_f32_e32 v21, v21, v35
	v_add_f32_e32 v22, 1.0, v22
	v_mul_f32_e32 v21, 0x3fb8aa3b, v21
	v_rcp_f32_e32 v22, v22
	v_exp_f32_e32 v85, v21
	v_add_f32_e32 v16, v16, v31
	v_mul_f32_e32 v16, 0xbfb8aa3b, v16
	v_exp_f32_e32 v16, v16
	v_mul_f32_e32 v22, v67, v22
	v_sqrt_f32_e32 v20, v20
	v_fma_f32 v21, -v85, v85, 1.0
	v_fma_f32 v24, v81, v24, v80
	v_mul_f32_e32 v82, v22, v20
	v_max_f32_e32 v21, 0, v21
	v_fma_f32 v20, v83, v24, v82
	v_add_f32_e32 v16, 1.0, v16
	v_rcp_f32_e32 v16, v16
	v_add_f32_e32 v23, v23, v33
	v_mul_f32_e32 v23, 0xbfb8aa3b, v23
	v_exp_f32_e32 v23, v23
	v_mul_f32_e32 v22, v83, v25
	v_mul_f32_e32 v16, 0xc1000000, v16
	v_mul_f32_e32 v16, v16, v35
	v_mul_f32_e32 v16, 0x3fb8aa3b, v16
	v_add_f32_e32 v23, 1.0, v23
	v_exp_f32_e32 v87, v16
	v_rcp_f32_e32 v23, v23
	v_add_f32_e32 v17, v17, v31
	v_mul_f32_e32 v17, 0xbfb8aa3b, v17
	v_fma_f32 v16, -v87, v87, 1.0
	v_exp_f32_e32 v17, v17
	v_sqrt_f32_e32 v21, v21
	v_mul_f32_e32 v23, v68, v23
	v_max_f32_e32 v16, 0, v16
	v_mul_f32_e32 v84, v23, v21
	v_mul_f32_e32 v21, v85, v22
	v_add_f32_e32 v17, 1.0, v17
	s_waitcnt lgkmcnt(2)
; DEVI float sigmoidf_(float x) { return __builtin_amdgcn_rcpf(1.f + __expf(-x)); }
; DEVI f32x4 mfma16(bf16x8 a, bf16x8 b, f32x4 c) { return __builtin_amdgcn_mfma_f32_16x16x32_bf16(a, b, c, 0, 0, 0); }
; DEVI void lru_item(const Params& p, int l, int item, int pass) {
;     ...
;     for (int mat = 0; mat < 2; ++mat) {
;       const u16* wb = WGT + (size_t)((((l * 2 + d) * 2 + mat) * 4 + n) * 64) * 64 + 8 * g;
;       f32x4 acc[4];
; #pragma unroll
;       for (int nt = 0; nt < 4; ++nt) {
;         const bf16x8 B0 = *(const bf16x8*)(wb + (16 * nt + fr) * 64), B1 = *(const bf16x8*)(wb + (16 * nt + fr) * 64 + 32);
;         f32x4 z = {0.f, 0.f, 0.f, 0.f};
;         z = mfma16(A0, B0, z); z = mfma16(A1, B1, z); acc[nt] = z;
;       }
;       asm volatile("s_waitcnt lgkmcnt(0)" ::: "memory");
; #pragma unroll
;       for (int nt = 0; nt < 4; ++nt)
; #pragma unroll
;         for (int j = 0; j < 4; ++j) exw[(4 * g + j) * 65 + 16 * nt + fr] = acc[nt][j];
;     ...
;     for (int q = 0; q < 16; ++q) {
;       const int tt = d == 0 ? q : 15 - q;
;       const float r = sigmoidf_(pre[0][tt] + ba), ig = sigmoidf_(pre[1][tt] + bx);
;       const float la = -8.f * r * sp;
;       const float a = __expf(la);
;       const float om = fmaxf(1.f - a * a, 0.f);
;       const float bb = sqrtf(om) * (ig * uo[tt]);
;       av[d][tt] = a; bv[d][tt] = bb;
;       Bp = a * Bp + bb; Ap *= a;
;     }
;     sm[((d * 8 + tg) * 64 + e) * 2 + 0] = Ap; sm[((d * 8 + tg) * 64 + e) * 2 + 1] = Bp;
	v_add_f32_e32 v18, v18, v33
	v_rcp_f32_e32 v17, v17
	v_mul_f32_e32 v18, 0xbfb8aa3b, v18
	v_exp_f32_e32 v18, v18
	v_mul_f32_e32 v17, 0xc1000000, v17
	v_mul_f32_e32 v17, v17, v35
	v_add_f32_e32 v18, 1.0, v18
	v_mul_f32_e32 v17, 0x3fb8aa3b, v17
	v_rcp_f32_e32 v18, v18
	v_exp_f32_e32 v89, v17
	v_add_f32_e32 v10, v10, v31
	v_mul_f32_e32 v10, 0xbfb8aa3b, v10
	v_exp_f32_e32 v10, v10
	v_mul_f32_e32 v18, v69, v18
	v_sqrt_f32_e32 v16, v16
	v_fma_f32 v17, -v89, v89, 1.0
	v_fma_f32 v20, v85, v20, v84
	v_mul_f32_e32 v86, v18, v16
	v_max_f32_e32 v17, 0, v17
	v_fma_f32 v16, v87, v20, v86
	v_add_f32_e32 v10, 1.0, v10
	v_rcp_f32_e32 v10, v10
	v_add_f32_e32 v19, v19, v33
	v_mul_f32_e32 v19, 0xbfb8aa3b, v19
	v_exp_f32_e32 v19, v19
	v_mul_f32_e32 v18, v87, v21
	v_mul_f32_e32 v10, 0xc1000000, v10
	v_mul_f32_e32 v10, v10, v35
	v_mul_f32_e32 v10, 0x3fb8aa3b, v10
	v_add_f32_e32 v19, 1.0, v19
	v_exp_f32_e32 v92, v10
	v_rcp_f32_e32 v19, v19
	v_add_f32_e32 v11, v11, v31
	v_mul_f32_e32 v11, 0xbfb8aa3b, v11
	v_fma_f32 v10, -v92, v92, 1.0
	v_exp_f32_e32 v11, v11
	v_sqrt_f32_e32 v17, v17
	v_mul_f32_e32 v19, v70, v19
	v_max_f32_e32 v10, 0, v10
	v_mul_f32_e32 v88, v19, v17
	v_mul_f32_e32 v17, v89, v18
	v_add_f32_e32 v11, 1.0, v11
	s_waitcnt lgkmcnt(1)
	v_add_f32_e32 v14, v14, v33
	v_rcp_f32_e32 v11, v11
	v_mul_f32_e32 v14, 0xbfb8aa3b, v14
	v_exp_f32_e32 v14, v14
	v_mul_f32_e32 v11, 0xc1000000, v11
	v_mul_f32_e32 v11, v11, v35
	v_add_f32_e32 v14, 1.0, v14
	v_mul_f32_e32 v11, 0x3fb8aa3b, v11
	v_rcp_f32_e32 v14, v14
	v_exp_f32_e32 v95, v11
	v_add_f32_e32 v8, v8, v31
	v_mul_f32_e32 v8, 0xbfb8aa3b, v8
	v_exp_f32_e32 v8, v8
	v_mul_f32_e32 v14, v71, v14
	v_sqrt_f32_e32 v10, v10
	v_fma_f32 v11, -v95, v95, 1.0
	v_fma_f32 v16, v89, v16, v88
	v_mul_f32_e32 v91, v14, v10
	v_max_f32_e32 v11, 0, v11
	v_fma_f32 v10, v92, v16, v91
	v_add_f32_e32 v8, 1.0, v8
	v_rcp_f32_e32 v8, v8
	v_add_f32_e32 v15, v15, v33
	v_mul_f32_e32 v15, 0xbfb8aa3b, v15
	v_exp_f32_e32 v15, v15
	v_mul_f32_e32 v14, v92, v17
	v_mul_f32_e32 v8, 0xc1000000, v8
	v_mul_f32_e32 v8, v8, v35
	v_mul_f32_e32 v8, 0x3fb8aa3b, v8
	v_add_f32_e32 v15, 1.0, v15
	v_exp_f32_e32 v101, v8
	v_rcp_f32_e32 v15, v15
	v_add_f32_e32 v9, v9, v31
	v_mul_f32_e32 v9, 0xbfb8aa3b, v9
	v_exp_f32_e32 v9, v9
	v_fma_f32 v8, -v101, v101, 1.0
	v_mul_f32_e32 v15, v73, v15
	v_sqrt_f32_e32 v11, v11
	v_max_f32_e32 v8, 0, v8
	v_mul_f32_e32 v93, v15, v11
	v_mul_f32_e32 v11, v95, v14
	v_add_f32_e32 v9, 1.0, v9
	v_rcp_f32_e32 v9, v9
	s_waitcnt lgkmcnt(0)
	v_add_f32_e32 v12, v12, v33
	v_mul_f32_e32 v12, 0xbfb8aa3b, v12
	v_exp_f32_e32 v12, v12
	v_mul_f32_e32 v9, 0xc1000000, v9
	v_mul_f32_e32 v9, v9, v35
	v_mul_f32_e32 v9, 0x3fb8aa3b, v9
	v_add_f32_e32 v12, 1.0, v12
	v_exp_f32_e32 v106, v9
	v_rcp_f32_e32 v12, v12
	v_fma_f32 v10, v95, v10, v93
	v_fma_f32 v9, -v106, v106, 1.0
	v_mul_f32_e32 v12, v74, v12
	v_max_f32_e32 v9, 0, v9
	v_sqrt_f32_e32 v8, v8
	s_nop 0
	v_mul_f32_e32 v94, v12, v8
	v_fma_f32 v8, v101, v10, v94
	v_mul_f32_e32 v10, v101, v11
	v_add_f32_e32 v11, v13, v33
	v_mul_f32_e32 v11, 0xbfb8aa3b, v11
	v_exp_f32_e32 v11, v11
	s_nop 0
	v_add_f32_e32 v11, 1.0, v11
	v_rcp_f32_e32 v11, v11
	s_mov_b64 s[0:1], 0x10000
	v_lshl_add_u64 v[24:25], v[28:29], 0, s[0:1]
	v_mul_f32_e32 v11, v72, v11
	v_lshlrev_b32_e32 v212, 1, v107
	v_sqrt_f32_e32 v9, v9
	s_nop 0
	v_mul_f32_e32 v96, v11, v9
	v_fma_f32 v9, v106, v8, v96
	v_mul_f32_e32 v8, v106, v10
	v_lshlrev_b32_e32 v10, 3, v76
	v_add_u32_e32 v76, 0, v10
	v_add_u32_e32 v10, 0x15b00, v76
	ds_write_b64 v10, v[8:9]
	v_lshl_add_u64 v[12:13], v[24:25], 0, v[212:213]
	global_load_dwordx4 v[8:11], v[12:13], off
	s_nop 0
	global_load_dwordx4 v[12:15], v[12:13], off offset:64
	s_waitcnt vmcnt(1)
	v_mfma_f32_16x16x32_bf16 v[8:11], v[4:7], v[8:11], 0
	v_mov_b32_e32 v35, v213
	v_lshl_add_u64 v[16:17], v[24:25], 0, v[34:35]
	v_mov_b32_e32 v31, v213
	s_waitcnt vmcnt(0)
	v_mfma_f32_16x16x32_bf16 v[8:11], v[0:3], v[12:15], v[8:11]
	global_load_dwordx4 v[12:15], v[16:17], off
	s_nop 0
	global_load_dwordx4 v[16:19], v[16:17], off offset:64
	v_lshl_add_u64 v[20:21], v[24:25], 0, v[30:31]
	v_mov_b32_e32 v33, v213
	s_waitcnt vmcnt(1)
	v_mfma_f32_16x16x32_bf16 v[12:15], v[4:7], v[12:15], 0
	v_lshl_add_u64 v[24:25], v[24:25], 0, v[32:33]
	s_mov_b64 s[0:1], 0x18000
	s_waitcnt vmcnt(0)
	v_mfma_f32_16x16x32_bf16 v[12:15], v[0:3], v[16:19], v[12:15]
	global_load_dwordx4 v[16:19], v[20:21], off
	s_nop 0
	global_load_dwordx4 v[20:23], v[20:21], off offset:64
	s_waitcnt vmcnt(1)
; DEVI f32x4 mfma16(bf16x8 a, bf16x8 b, f32x4 c) { return __builtin_amdgcn_mfma_f32_16x16x32_bf16(a, b, c, 0, 0, 0); }
; DEVI void lru_item(const Params& p, int l, int item, int pass) {
;     ...
;     for (int mat = 0; mat < 2; ++mat) {
;       const u16* wb = WGT + (size_t)((((l * 2 + d) * 2 + mat) * 4 + n) * 64) * 64 + 8 * g;
;       f32x4 acc[4];
; #pragma unroll
;       for (int nt = 0; nt < 4; ++nt) {
;         const bf16x8 B0 = *(const bf16x8*)(wb + (16 * nt + fr) * 64), B1 = *(const bf16x8*)(wb + (16 * nt + fr) * 64 + 32);
;         f32x4 z = {0.f, 0.f, 0.f, 0.f};
;         z = mfma16(A0, B0, z); z = mfma16(A1, B1, z); acc[nt] = z;
;       }
;       asm volatile("s_waitcnt lgkmcnt(0)" ::: "memory");
; #pragma unroll
;       for (int nt = 0; nt < 4; ++nt)
; #pragma unroll
;         for (int j = 0; j < 4; ++j) exw[(4 * g + j) * 65 + 16 * nt + fr] = acc[nt][j];
;       asm volatile("s_waitcnt lgkmcnt(0)" ::: "memory");
; #pragma unroll
;       for (int tt = 0; tt < 16; ++tt) pre[mat][tt] = exw[tt * 65 + lane];
;     }
;     const float ba = p.in[14][(l * 2 + d) * 256 + c], bx = p.in[16][(l * 2 + d) * 256 + c];
;     const float lam = p.in[17][(l * 2 + d) * 256 + c];
;     const float exl = __expf(-lam); const float sp = exl < 0.03f ? exl * (1.f - exl * (0.5f - exl * (0.33333334f - 0.25f * exl))) : __logf(1.f + exl);
	v_mfma_f32_16x16x32_bf16 v[16:19], v[4:7], v[16:19], 0
	s_waitcnt vmcnt(0)
	v_mfma_f32_16x16x32_bf16 v[16:19], v[0:3], v[20:23], v[16:19]
	global_load_dwordx4 v[20:23], v[24:25], off
	s_nop 0
	global_load_dwordx4 v[24:27], v[24:25], off offset:64
	s_waitcnt lgkmcnt(0)
	s_waitcnt vmcnt(1)
	v_mfma_f32_16x16x32_bf16 v[20:23], v[4:7], v[20:23], 0
	s_waitcnt vmcnt(0)
	v_mfma_f32_16x16x32_bf16 v[20:23], v[0:3], v[24:27], v[20:23]
	v_add_u32_e32 v24, v90, v108
	v_add_u32_e32 v90, 0xd800, v24
	v_add_u32_e32 v107, 0xdc00, v24
	ds_write2_b32 v90, v8, v12 offset0:64 offset1:80
	ds_write2_b32 v90, v9, v13 offset0:129 offset1:145
	ds_write2_b32 v90, v10, v14 offset0:194 offset1:210
	ds_write2_b32 v107, v11, v15 offset0:3 offset1:19
	s_nop 0
	ds_write2_b32 v90, v16, v20 offset0:96 offset1:112
	ds_write2_b32 v90, v17, v21 offset0:161 offset1:177
	ds_write2_b32 v90, v18, v22 offset0:226 offset1:242
	ds_write2_b32 v107, v19, v23 offset0:35 offset1:51
	v_lshl_add_u64 v[18:19], v[28:29], 0, s[0:1]
	s_waitcnt lgkmcnt(0)
	v_lshl_add_u64 v[22:23], v[18:19], 0, v[212:213]
	ds_read2_b32 v[8:9], v97 offset0:64 offset1:129
	ds_read2_b32 v[10:11], v98 offset0:66 offset1:131
	ds_read2_b32 v[12:13], v99 offset0:68 offset1:133
	ds_read2_b32 v[14:15], v100 offset0:70 offset1:135
	ds_read2_b32 v[16:17], v102 offset0:72 offset1:137
	ds_read2_b32 v[20:21], v103 offset0:74 offset1:139
	ds_read2_b32 v[24:25], v104 offset0:76 offset1:141
	ds_read2_b32 v[42:43], v105 offset0:78 offset1:143
	global_load_dwordx4 v[26:29], v[22:23], off
	global_load_dwordx4 v[108:111], v[22:23], off offset:64
	s_waitcnt vmcnt(1)
	v_mfma_f32_16x16x32_bf16 v[26:29], v[4:7], v[26:29], 0
	v_lshl_add_u64 v[22:23], v[18:19], 0, v[34:35]
	s_mov_b32 s0, 0x3cf5c28f
	s_waitcnt vmcnt(0)
	v_mfma_f32_16x16x32_bf16 v[26:29], v[0:3], v[108:111], v[26:29]
	global_load_dwordx4 v[108:111], v[22:23], off
	global_load_dwordx4 v[112:115], v[22:23], off offset:64
	v_lshl_add_u64 v[22:23], v[18:19], 0, v[30:31]
	v_lshl_add_u64 v[18:19], v[18:19], 0, v[32:33]
	s_waitcnt vmcnt(1)
	v_mfma_f32_16x16x32_bf16 v[108:111], v[4:7], v[108:111], 0
	s_waitcnt vmcnt(0)
	v_mfma_f32_16x16x32_bf16 v[108:111], v[0:3], v[112:115], v[108:111]
	global_load_dwordx4 v[112:115], v[22:23], off
	global_load_dwordx4 v[116:119], v[22:23], off offset:64
	s_waitcnt vmcnt(1)
	v_mfma_f32_16x16x32_bf16 v[112:115], v[4:7], v[112:115], 0
	s_waitcnt vmcnt(0)
	v_mfma_f32_16x16x32_bf16 v[112:115], v[0:3], v[116:119], v[112:115]
	global_load_dwordx4 v[30:33], v[18:19], off
	global_load_dwordx4 v[116:119], v[18:19], off offset:64
	s_waitcnt lgkmcnt(0)
	s_waitcnt vmcnt(1)
	v_mfma_f32_16x16x32_bf16 v[4:7], v[4:7], v[30:33], 0
	s_waitcnt vmcnt(0)
	v_mfma_f32_16x16x32_bf16 v[0:3], v[0:3], v[116:119], v[4:7]
	ds_write2_b32 v90, v26, v108 offset0:64 offset1:80
	ds_write2_b32 v90, v27, v109 offset0:129 offset1:145
	ds_write2_b32 v90, v28, v110 offset0:194 offset1:210
	ds_write2_b32 v107, v29, v111 offset0:3 offset1:19
	s_nop 3
	ds_write2_b32 v90, v112, v0 offset0:96 offset1:112
	ds_write2_b32 v90, v113, v1 offset0:161 offset1:177
	ds_write2_b32 v90, v114, v2 offset0:226 offset1:242
	ds_write2_b32 v107, v115, v3 offset0:35 offset1:51
	s_waitcnt lgkmcnt(0)
	ds_read2_b32 v[0:1], v97 offset0:64 offset1:129
	ds_read2_b32 v[2:3], v98 offset0:66 offset1:131
	ds_read2_b32 v[4:5], v99 offset0:68 offset1:133
	ds_read2_b32 v[6:7], v100 offset0:70 offset1:135
	ds_read2_b32 v[18:19], v102 offset0:72 offset1:137
	ds_read2_b32 v[22:23], v103 offset0:74 offset1:139
	ds_read2_b32 v[26:27], v104 offset0:76 offset1:141
	ds_read2_b32 v[28:29], v105 offset0:78 offset1:143
	s_waitcnt vmcnt(0)
	v_mov_b32_e32 v32, v140
	v_mov_b32_e32 v31, v141
	v_mov_b32_e32 v30, v142
	s_waitcnt vmcnt(0)
	v_mul_f32_e32 v30, 0xbfb8aa3b, v30
	v_exp_f32_e32 v30, v30
	s_nop 0
	v_cmp_ngt_f32_e32 vcc, s0, v30
	s_and_saveexec_b64 s[0:1], vcc
	s_xor_b64 s[8:9], exec, s[0:1]
	s_cbranch_execz .LBB0_1561
	v_add_f32_e32 v30, 1.0, v30
	v_cmp_gt_f32_e32 vcc, s63, v30
	s_mov_b32 s0, 0x3f317217
	s_nop 0
	v_cndmask_b32_e64 v33, 0, 32, vcc
	v_ldexp_f32 v30, v30, v33
	v_log_f32_e32 v30, v30
	s_nop 0
	v_mul_f32_e32 v33, 0x3f317217, v30
	v_fma_f32 v33, v30, s0, -v33
	v_fmac_f32_e32 v33, 0x3377d1cf, v30
	s_mov_b32 s0, 0x7f800000
	v_fmac_f32_e32 v33, 0x3f317217, v30
	v_cmp_lt_f32_e64 s[6:7], |v30|, s0
	s_nop 1
	v_cndmask_b32_e64 v30, v30, v33, s[6:7]
	v_cndmask_b32_e32 v33, 0, v225, vcc
	v_sub_f32_e32 v33, v30, v33
